# speedup vs baseline: 1.0194x; 1.0021x over previous
; __device__ __forceinline__ float shfl_idx(float v, int srclane) { return __int_as_float(__builtin_amdgcn_ds_bpermute(srclane << 2, __float_as_int(v))); }
; __device__ __forceinline__ float sigmoidf_(float x) { return __frcp_rn(1.f + __expf(-x)); }
; __device__ __forceinline__ float softplusf_(float x) { return fmaxf(x, 0.f) + log1pf(expf(-fabsf(x))); }
; __device__ __forceinline__ void prepB(const Params& p, int h, int n, char* shmc, int tid, int wv) {
;   float* kF = (float*)shmc;
;   float* vF = kF + 8192;
;   u16* qB = (u16*)(vF + 8192);
;   u16* kB = qB + 64 * 136;
;   float* Mm = (float*)(kB + 64 * 136);
;   float* gcS = Mm + 4096;
;   float* betaS = gcS + 64;
;   const u16* GQKV = (const u16*)(p.ws + O_GQKV * MiB);
;   const float* GAB = (const float*)(p.ws + O_GAB * MiB);
;   u16* WNB = (u16*)(p.ws + O_WNB * MiB);
;   u16* UTB = (u16*)(p.ws + O_UTB * MiB);
;   u16* QPB = (u16*)(p.ws + O_QPB * MiB);
;   u16* KDTB = (u16*)(p.ws + O_KDTB * MiB);
;   u16* PB = (u16*)(p.ws + O_PB * MiB);
;   float* DB = (float*)(p.ws + O_DB * MiB);
;   const long rowbase = (long)n * 64;
;   const int tix = h * 256 + n;
;   if (tid < 64) {
;     const int t = tid;
;     const float ga = GAB[(rowbase + t) * 16 + h], gb = GAB[(rowbase + t) * 16 + 8 + h];
;     float g = -__expf(p.a_a_log[h]) * softplusf_(ga + p.a_dt_bias[h]);
; #pragma unroll
;     for (int o = 1; o < 64; o <<= 1) { const float v = shfl_idx(g, t - o); if (t >= o) g += v; }
;     gcS[t] = g;
;     betaS[t] = sigmoidf_(gb);
;   }
;   __syncthreads();
;   {
;     const int cgi = tid & 15, c0 = cgi * 8, t0 = (tid >> 4) * 2;
; __global__ __launch_bounds__(512) void mk(Params p_arg, int ph0, int ph1) {
;     ...
;     if (ph == 2) {
;       for (int tile = blockIdx.x; tile < 4096; tile += gridDim.x) {
;         const int rnd = tile >> 8, idx = ((rnd >> 1) << 8) | (tile & 255), h = idx & 7, n = idx >> 3;
;     ...
;         if (rnd & 1) prepB(p, h, n, shmc, tid, wv);
;     ...
;         if (!(rnd & 1)) prepA(p, h, n, shmc, tid, wv);
;     ...
;       }
.LBB0_427:
	s_and_b64 vcc, exec, s[8:9]
	s_cbranch_vccz .LBB0_550
	s_cmp_lg_u32 s3, 2
	s_cbranch_scc1 .LBB0_550
	v_readlane_b32 s8, v253, 14
	v_readlane_b32 s9, v253, 15
	s_andn2_b64 vcc, exec, s[8:9]
	s_cbranch_vccnz .LBB0_550
	v_cmp_gt_i32_e64 s[8:9], 64, v214
	s_waitcnt vmcnt(0)
	v_lshrrev_b32_e32 v2, 5, v214
	v_and_b32_e32 v2, 0x7ffffc, v2
	v_writelane_b32 v254, s8, 37
	v_lshrrev_b32_e32 v4, 2, v214
	v_and_or_b32 v2, v4, 3, v2
	v_writelane_b32 v254, s9, 38
	v_cmp_gt_i32_e64 s[8:9], 1, v214
	v_lshlrev_b32_e32 v4, 8, v214
	v_ashrrev_i32_e32 v40, 3, v214
	v_writelane_b32 v254, s8, 39
	v_and_b32_e32 v4, 0x100, v4
	v_lshlrev_b32_e32 v2, 9, v2
	v_writelane_b32 v254, s9, 40
	v_cmp_gt_i32_e64 s[8:9], 2, v214
	v_and_b32_e32 v5, 0x70, v214
	v_or3_b32 v46, v4, v5, v2
	v_writelane_b32 v254, s8, 41
	v_or_b32_e32 v5, 1, v40
	v_lshlrev_b32_e32 v6, 3, v5
	v_writelane_b32 v254, s9, 42
	v_cmp_gt_i32_e64 s[8:9], 4, v214
	v_and_b32_e32 v6, 0x78, v6
	v_or3_b32 v48, v4, v6, v2
	v_writelane_b32 v254, s8, 43
	v_and_b32_e32 v2, 15, v214
	v_bfe_u32 v4, v214, 4, 2
	v_writelane_b32 v254, s9, 44
	v_cmp_gt_i32_e64 s[8:9], 8, v214
	s_mov_b32 s7, 0x14400
	v_lshlrev_b32_e32 v7, 3, v4
	v_writelane_b32 v254, s8, 45
	v_lshlrev_b32_e32 v13, 4, v4
	v_readlane_b32 s10, v253, 17
	v_writelane_b32 v254, s9, 46
	v_cmp_gt_i32_e64 s[8:9], 16, v214
	v_lshlrev_b32_e32 v4, 2, v4
	v_or_b32_e32 v8, s10, v2
	v_writelane_b32 v254, s8, 47
	v_lshlrev_b32_e32 v1, 2, v214
	s_mov_b32 s3, 0x1c800
	v_writelane_b32 v254, s9, 48
	v_cmp_gt_i32_e64 s[8:9], 32, v214
	v_lshlrev_b32_e32 v10, 8, v8
	s_addk_i32 s3, 0x110
	v_writelane_b32 v254, s8, 49
	v_and_b32_e32 v50, 3, v214
	v_lshlrev_b32_e32 v58, 4, v50
	v_writelane_b32 v254, s9, 50
	v_readlane_b32 s9, v253, 16
	s_add_i32 s8, s7, 0x110
	s_mov_b32 s7, 0x10000
	v_or_b32_e32 v12, s9, v2
	v_mul_u32_u24_e32 v6, 0x88, v12
	v_add_lshl_u32 v6, v6, v7, 1
	s_addk_i32 s7, 0x110
	v_add_u32_e32 v7, 64, v6
	v_add_u32_e32 v167, s8, v6
	v_add_u32_e32 v168, s7, v6
	v_add_u32_e32 v170, s8, v7
	v_add_u32_e32 v171, s7, v7
	v_add_u32_e32 v7, 0x80, v6
	v_add_u32_e32 v6, 0xc0, v6
	v_add_u32_e32 v174, s8, v6
	v_add_u32_e32 v175, s7, v6
	v_or_b32_e32 v6, s9, v4
	v_readlane_b32 s9, v253, 18
	v_cmp_gt_u32_e64 s[16:17], v8, v6
	v_readlane_b32 s11, v254, 14
	v_readlane_b32 s10, v254, 9
	v_add_u32_e32 v172, s8, v7
	v_add_u32_e32 v173, s7, v7
	v_and_or_b32 v7, v1, 48, s9
	v_writelane_b32 v254, s16, 51
	v_or_b32_e32 v4, v7, v4
	s_mov_b32 s9, 0x18800
	v_writelane_b32 v254, s17, 52
	v_cmp_lt_u32_e64 s[16:17], v8, v6
	v_lshlrev_b32_e32 v52, 3, v4
	v_or_b32_e32 v4, 1, v6
	v_writelane_b32 v254, s16, 53
	s_add_i32 s14, s9, 0x110
	v_lshlrev_b32_e32 v11, 2, v6
	v_writelane_b32 v254, s17, 54
	v_cmp_gt_u32_e64 s[16:17], v8, v4
	v_add3_u32 v179, s14, v10, v11
	v_lshlrev_b32_e32 v10, 2, v4
	v_writelane_b32 v254, s16, 55
	v_add_u32_e32 v180, s3, v10
	v_add_u32_e32 v181, s11, v10
	v_writelane_b32 v254, s17, 56
	v_cmp_le_u32_e64 s[16:17], v8, v4
	v_and_or_b32 v10, v4, 13, v7
	v_lshlrev_b32_e32 v54, 3, v10
	v_writelane_b32 v254, s16, 57
	v_or_b32_e32 v10, 2, v6
	v_and_or_b32 v7, v10, 14, v7
	v_writelane_b32 v254, s17, 58
	v_cmp_gt_u32_e64 s[16:17], v8, v10
	v_lshlrev_b32_e32 v56, 3, v7
	v_or_b32_e32 v7, 3, v6
	v_writelane_b32 v254, s16, 59
	v_lshlrev_b32_e32 v14, 2, v10
	v_or_b32_e32 v2, s10, v2
	v_writelane_b32 v254, s17, 60
	v_cmp_le_u32_e64 s[16:17], v8, v10
	v_add_u32_e32 v182, s3, v14
	v_add_u32_e32 v183, s11, v14
	v_writelane_b32 v254, s16, 61
	v_lshlrev_b32_e32 v14, 2, v7
	v_add_u32_e32 v67, s11, v1
	v_writelane_b32 v254, s17, 62
	v_cmp_lt_u32_e64 s[16:17], v8, v10
	v_add_u32_e32 v178, s11, v11
	v_add_u32_e32 v185, s11, v14
	v_writelane_b32 v254, s16, 63
	v_cmp_gt_u32_e64 s[10:11], v2, v6
	v_cmp_le_u32_e64 s[64:65], v2, v7
	v_writelane_b32 v255, s17, 0
	v_cmp_gt_u32_e64 s[16:17], v8, v7
	v_and_b32_e32 v194, 0x7f, v214
	v_ashrrev_i32_e32 v199, 7, v214
	v_writelane_b32 v255, s16, 1
	v_add_u32_e32 v51, -4, v1
	v_add_u32_e32 v53, -8, v1
	v_writelane_b32 v255, s17, 2
	v_cmp_le_u32_e64 s[16:17], v8, v7
	v_add_u32_e32 v55, -16, v1
	v_subrev_u32_e32 v57, 32, v1
	v_writelane_b32 v255, s16, 3
	v_subrev_u32_e32 v59, 64, v1
	v_add_u32_e32 v63, 0xffffff80, v1
	v_writelane_b32 v255, s17, 4
	v_cmp_lt_u32_e64 s[16:17], v8, v7
	v_add_u32_e32 v65, s3, v1
	v_bitop3_b32 v157, v1, 4, v239 bitop3:0x6c
	v_writelane_b32 v255, s16, 5
	v_bitop3_b32 v158, v1, 8, v239 bitop3:0x6c
	v_bitop3_b32 v159, v1, 16, v239 bitop3:0x6c
	v_writelane_b32 v255, s17, 6
	v_writelane_b32 v255, s10, 7
	v_cmp_lt_u32_e64 s[16:17], v2, v7
	v_bitop3_b32 v160, v1, 32, v239 bitop3:0x6c
	v_writelane_b32 v255, s11, 8
	v_cmp_lt_u32_e64 s[10:11], v2, v6
	s_movk_i32 s12, 0x110
	v_cmp_le_u32_e64 s[24:25], v8, v6
	v_writelane_b32 v255, s10, 9
	v_cmp_le_u32_e64 s[48:49], v2, v6
	v_cmp_le_u32_e64 s[26:27], v2, v4
	v_writelane_b32 v255, s11, 10
	v_cmp_gt_u32_e64 s[10:11], v2, v4
	v_and_b32_e32 v4, -4, v214
	v_lshlrev_b32_e32 v6, 13, v50
	v_writelane_b32 v255, s10, 11
	s_movk_i32 s9, 0x100
	v_lshlrev_b32_e32 v29, 2, v194
	v_writelane_b32 v255, s11, 12
	v_cmp_gt_u32_e64 s[10:11], v2, v7
	v_or_b32_e32 v7, 4, v58
	v_lshlrev_b32_e32 v17, 9, v7
	v_lshl_add_u32 v191, v7, 2, s3
	v_or_b32_e32 v7, 8, v58
	v_lshlrev_b32_e32 v21, 9, v7
	v_lshl_add_u32 v192, v7, 2, s3
	v_or_b32_e32 v7, 12, v58
	v_and_b32_e32 v72, 4, v1
	v_lshlrev_b32_e32 v1, 13, v199
	v_add_u32_e32 v189, 0x110, v4
	v_lshlrev_b32_e32 v25, 9, v7
	v_lshl_add_u32 v193, v7, 2, s3
	v_cmp_gt_i32_e64 s[18:19], s9, v214
	s_mov_b32 s9, 0x8000
; __device__ __forceinline__ uint4 ldg16(const void* p) { const u32x4 v = *(const __attribute__((address_space(1))) u32x4*)(p); return make_uint4(v.x, v.y, v.z, v.w); }
; __device__ __forceinline__ void prepB(const Params& p, int h, int n, char* shmc, int tid, int wv) {
;     ...
;   {
;     const int cgi = tid & 15, c0 = cgi * 8, t0 = (tid >> 4) * 2;
; #pragma unroll
;     for (int sig = 0; sig < 3; ++sig) {
;       const int colg = sig * 1024 + h * 128 + c0;
;       uint4 rawv[5];
; #pragma unroll
;       for (int rr = 0; rr < 5; ++rr) {
;         const long tok = rowbase + t0 - 3 + rr;
;         rawv[rr] = make_uint4(0u, 0u, 0u, 0u);
;         if (tok >= 0) rawv[rr] = ldg16(GQKV + tok * 3072 + colg);
;       }
;       float w[4][8];
; #pragma unroll
;       for (int j = 0; j < 4; ++j) {
;         const float4 wa = *(const float4*)(p.a_conv_w + j * 3072 + colg), wb = *(const float4*)(p.a_conv_w + j * 3072 + colg + 4);
;         w[j][0] = wa.x; w[j][1] = wa.y; w[j][2] = wa.z; w[j][3] = wa.w; w[j][4] = wb.x; w[j][5] = wb.y; w[j][6] = wb.z; w[j][7] = wb.w;
;       }
	v_lshlrev_b32_e32 v7, 4, v214
	v_add3_u32 v198, s12, v6, v4
	v_or_b32_e32 v4, v1, v29
	v_mul_lo_u32 v166, v8, s12
	v_mul_lo_u32 v169, v2, s12
	v_lshl_add_u32 v176, v8, 2, s3
	v_lshlrev_b32_e32 v8, 8, v2
	v_lshl_add_u32 v186, v2, 2, s3
	v_cmp_gt_u32_e64 s[28:29], v2, v10
	v_cmp_le_u32_e64 s[30:31], v2, v10
	v_cmp_lt_u32_e64 s[90:91], v2, v10
	v_lshlrev_b32_e32 v2, 2, v50
	s_addk_i32 s9, 0x110
	v_add_u32_e32 v200, 0x110, v4
	v_and_b32_e32 v4, 0x70, v7
	v_add_u32_e32 v184, s3, v14
	v_and_b32_e32 v64, 4, v2
	v_or_b32_e32 v14, 0x200, v6
	v_or_b32_e32 v15, 0x400, v6
	v_or_b32_e32 v16, 0x600, v6
	v_or_b32_e32 v18, 0xa00, v6
	v_or_b32_e32 v19, 0xc00, v6
	v_or_b32_e32 v20, 0xe00, v6
	v_or_b32_e32 v66, 8, v2
	v_or_b32_e32 v22, 0x1200, v6
	v_or_b32_e32 v23, 0x1400, v6
	v_or_b32_e32 v24, 0x1600, v6
	v_or_b32_e32 v26, 0x1a00, v6
	v_or_b32_e32 v27, 0x1c00, v6
	v_or_b32_e32 v28, 0x1e00, v6
	v_or_b32_e32 v68, 24, v2
	v_mov_b32_e32 v2, s9
	s_movk_i32 s9, 0x7f
	v_add_u32_e32 v197, v189, v6
	v_add3_u32 v201, s12, v1, v29
	v_lshlrev_b32_e32 v1, 8, v40
	v_lshlrev_b32_e32 v6, 1, v4
	v_cmp_lt_i32_e64 s[72:73], s9, v214
	v_add3_u32 v202, s14, v1, v6
	v_lshlrev_b32_e32 v1, 2, v4
	v_and_b32_e32 v42, -2, v40
	v_lshl_add_u32 v163, v5, 2, s3
	v_mul_lo_u32 v164, v5, s12
	v_lshlrev_b32_e32 v5, 9, v5
	v_cndmask_b32_e64 v2, v2, v236, s[72:73]
	v_lshl_or_b32 v6, v40, 9, v1
	s_movk_i32 s9, 0x88
	v_mul_lo_u32 v162, v42, s12
	v_add_u32_e32 v195, v2, v29
	v_and_b32_e32 v70, 0xffffff80, v7
	v_and_b32_e32 v2, 0x60, v7
	v_add_u32_e32 v203, 0x110, v6
	v_mad_u64_u32 v[6:7], s[12:13], v40, s9, v[4:5]
	v_add_u32_e32 v204, 0x110, v1
	v_lshlrev_b32_e32 v1, 1, v6
	v_add_u32_e32 v205, s7, v1
	v_add_u32_e32 v206, s8, v1
	v_and_b32_e32 v7, 0x3ffffff8, v214
	v_add_u32_e32 v1, 16, v1
	v_sub_u32_e32 v6, v6, v7
	v_add_u32_e32 v208, s7, v1
	v_add_u32_e32 v209, s8, v1
	v_ashrrev_i32_e32 v1, 5, v214
	v_lshl_add_u32 v207, v6, 2, v236
	v_and_b32_e32 v1, 0x3ffffffc, v1
	v_lshrrev_b32_e32 v6, 1, v214
	v_and_or_b32 v1, v6, 3, v1
	v_lshlrev_b32_e32 v6, 2, v1
	v_or_b32_e32 v10, 1, v6
	v_lshlrev_b32_e32 v0, 3, v214
	v_add_u32_e32 v177, s3, v11
	v_add3_u32 v187, s14, v8, v11
	v_ashrrev_i32_e32 v7, 31, v6
	v_ashrrev_i32_e32 v11, 31, v10
	v_and_b32_e32 v69, 0x78, v0
	v_lshlrev_b64 v[76:77], 11, v[6:7]
	v_lshlrev_b64 v[78:79], 11, v[10:11]
	v_or_b32_e32 v10, 2, v6
	v_or_b32_e32 v6, 3, v6
	v_lshlrev_b32_e32 v0, 1, v69
	v_ashrrev_i32_e32 v188, 2, v214
	v_ashrrev_i32_e32 v7, 31, v6
	v_add_u32_e32 v73, s8, v0
	v_add_u32_e32 v156, s7, v0
	v_lshlrev_b32_e32 v0, 1, v214
	v_lshlrev_b32_e32 v60, 6, v188
	v_lshlrev_b64 v[82:83], 11, v[6:7]
	v_lshlrev_b32_e32 v1, 1, v188
	v_lshlrev_b32_e32 v6, 12, v50
	v_ashrrev_i32_e32 v43, 31, v42
	v_lshl_add_u32 v3, v69, 2, v236
	v_and_b32_e32 v0, 4, v0
	v_lshlrev_b32_e32 v9, 9, v42
	v_lshlrev_b32_e32 v74, 4, v199
	v_and_b32_e32 v8, 0x78, v214
	v_ashrrev_i32_e32 v11, 31, v10
	v_add3_u32 v210, s14, v1, v6
	v_add3_u32 v211, s14, v6, v1
	v_and_b32_e32 v6, 64, v60
	v_mul_u32_u24_e32 v1, 0x110, v12
	v_ashrrev_i32_e32 v215, 31, v214
	v_lshl_add_u64 v[44:45], v[42:43], 0, -3
	v_lshl_add_u32 v161, v42, 2, s3
	v_ashrrev_i32_e32 v47, 31, v46
	v_ashrrev_i32_e32 v49, 31, v48
	v_add_u32_e32 v165, s8, v13
	v_ashrrev_i32_e32 v61, 31, v60
	v_and_b32_e32 v62, 32, v58
	v_lshl_add_u32 v190, v50, 6, s3
	v_cmp_eq_u32_e64 s[68:69], 0, v50
	v_ashrrev_i32_e32 v71, 31, v70
	v_lshl_add_u32 v196, v214, 6, v236
	v_ashrrev_i32_e32 v75, 31, v74
	v_cmp_lt_i32_e64 s[20:21], 0, v199
	v_ashrrev_i32_e32 v41, 31, v40
	v_mov_b32_e32 v232, 0x110
	v_lshlrev_b64 v[80:81], 11, v[10:11]
	v_writelane_b32 v255, s14, 13
	v_add_u32_e32 v216, 0x200, v210
	v_add_u32_e32 v217, 0x400, v210
	v_add_u32_e32 v218, 0x600, v210
	v_add_u32_e32 v219, 0x800, v210
	v_add_u32_e32 v220, 0xa00, v210
	v_add_u32_e32 v221, 0xc00, v210
	v_add_u32_e32 v222, 0xe00, v210
	v_add3_u32 v223, s7, v1, v13
	v_add_u32_e32 v224, s3, v29
	v_lshlrev_b32_e32 v84, 1, v0
	v_add_u32_e32 v225, v189, v14
	v_add_u32_e32 v226, v189, v15
	v_add_u32_e32 v227, v189, v16
	v_add_u32_e32 v228, v189, v17
	v_add_u32_e32 v229, v189, v18
	v_add_u32_e32 v244, v189, v19
	v_add_u32_e32 v245, v189, v20
	v_add_u32_e32 v246, v189, v21
	v_add_u32_e32 v247, v189, v22
	v_add_u32_e32 v248, v189, v23
	v_add_u32_e32 v249, v189, v24
	v_add_u32_e32 v250, v189, v25
	v_add_u32_e32 v251, v189, v26
	v_add_u32_e32 v252, v189, v27
	v_add_u32_e32 v236, v189, v28
	v_lshlrev_b32_e32 v86, 1, v2
	v_lshlrev_b32_e32 v88, 1, v4
	v_lshlrev_b32_e32 v90, 1, v8
	v_lshlrev_b32_e32 v92, 1, v6
	v_add_u32_e32 v240, v3, v9
	v_add_u32_e32 v241, v3, v5
	v_mov_b64_e32 v[242:243], s[62:63]
	flat_load_dwordx2 v[242:243], v[242:243] offset:24
	s_and_b32 s8, s2, 7
	s_lshl_b32 s8, s8, 7
	v_and_b32_e32 v234, 0x7f, v214
	v_lshrrev_b32_e32 v235, 7, v214
	v_mul_u32_u24_e32 v235, 0xc00, v235
	v_add3_u32 v234, v234, v235, s8
	v_lshlrev_b32_e32 v234, 2, v234
	v_add_u32_e32 v235, 0x1000, v234
	s_waitcnt vmcnt(0) lgkmcnt(0)
	v_readfirstlane_b32 s14, v242
	v_readfirstlane_b32 s15, v243
	v_add_u32_e32 v242, 0x2000, v234
	s_nop 3
	s_nop 1
	global_load_dword v233, v234, s[14:15]
	global_load_dword v243, v235, s[14:15]
	global_load_dword v242, v242, s[14:15]
	v_lshlrev_b32_e32 v234, 2, v214
	v_add_u32_e32 v234, 0x1e110, v234
	s_waitcnt vmcnt(0)
	ds_write_b32 v234, v233
	ds_write_b32 v234, v243 offset:2048
	ds_write_b32 v234, v242 offset:4096
	s_waitcnt lgkmcnt(0)
	v_and_b32_e32 v233, 15, v214
	v_lshlrev_b32_e32 v233, 5, v233
	v_add_u32_e32 v233, 0x1e110, v233
	s_mov_b32 s7, s2
	s_branch .LBB0_433

; __device__ __forceinline__ float bflo(unsigned w) { return __uint_as_float(w << 16); }
; __device__ __forceinline__ float bfhi(unsigned w) { return __uint_as_float(w & 0xffff0000u); }
; __device__ __forceinline__ float sigmoidf_(float x) { return __frcp_rn(1.f + __expf(-x)); }
; __device__ __forceinline__ void prepB(const Params& p, int h, int n, char* shmc, int tid, int wv) {
;     ...
;       float w[4][8];
; #pragma unroll
;       for (int j = 0; j < 4; ++j) {
;         const float4 wa = *(const float4*)(p.a_conv_w + j * 3072 + colg), wb = *(const float4*)(p.a_conv_w + j * 3072 + colg + 4);
;         w[j][0] = wa.x; w[j][1] = wa.y; w[j][2] = wa.z; w[j][3] = wa.w; w[j][4] = wb.x; w[j][5] = wb.y; w[j][6] = wb.z; w[j][7] = wb.w;
;       }
;       float out[2][8];
; #pragma unroll
;       for (int tt = 0; tt < 2; ++tt)
; #pragma unroll
;         for (int i = 0; i < 8; ++i) out[tt][i] = 0.f;
; #pragma unroll
;       for (int rr = 0; rr < 5; ++rr) {
;         const uint4 raw = rawv[rr];
;         const unsigned rw[4] = {raw.x, raw.y, raw.z, raw.w};
;         float xv[8];
; #pragma unroll
;         for (int i = 0; i < 4; ++i) { xv[2 * i] = bflo(rw[i]); xv[2 * i + 1] = bfhi(rw[i]); }
; #pragma unroll
;         for (int tt = 0; tt < 2; ++tt) {
;           const int j = rr - tt;
;           if (j >= 0 && j < 4) {
; #pragma unroll
;             for (int i = 0; i < 8; ++i) out[tt][i] += w[j][i] * xv[i];
;           }
;         }
;       }
; #pragma unroll
;       for (int tt = 0; tt < 2; ++tt) {
;         const int t = t0 + tt;
;         float ss = 0.f;
; #pragma unroll
;         for (int i = 0; i < 8; ++i) { const float o = out[tt][i]; out[tt][i] = o * sigmoidf_(o); ss += out[tt][i] * out[tt][i]; }
.LBB0_446:
	s_or_b64 exec, exec, s[14:15]
	s_waitcnt vmcnt(0)
	s_mov_b64 s[14:15], exec
	s_and_b64 exec, s[14:15], s[80:81]
	v_mov_b32_e32 v1, v14
	v_mov_b32_e32 v24, v15
	v_mov_b32_e32 v25, v16
	v_mov_b32_e32 v26, v17
	s_and_b64 exec, s[14:15], s[82:83]
	v_mov_b32_e32 v27, v10
	v_mov_b32_e32 v29, v11
	v_mov_b32_e32 v28, v12
	v_mov_b32_e32 v30, v13
	s_and_b64 exec, s[14:15], s[84:85]
	v_mov_b32_e32 v31, v18
	v_mov_b32_e32 v32, v19
	v_mov_b32_e32 v33, v20
	v_mov_b32_e32 v89, v21
	s_mov_b64 exec, s[14:15]
	s_lshl_b32 s3, s37, 8
	s_add_i32 s14, s12, s3
	s_ashr_i32 s15, s14, 31
	s_lshl_b64 s[8:9], s[14:15], 14
	v_lshl_add_u64 v[22:23], v[94:95], 0, s[8:9]
	v_mov_b32_e32 v85, v213
	v_lshl_add_u64 v[22:23], v[22:23], 0, v[84:85]
	v_lshl_add_u64 v[102:103], v[22:23], 0, s[44:45]
	v_lshlrev_b32_e32 v212, 2, v87
	v_and_b32_e32 v141, 0xffff0000, v24
	v_and_b32_e32 v121, 0xffff0000, v25
	v_and_b32_e32 v123, 0xffff0000, v26
	s_waitcnt vmcnt(0)
	v_lshlrev_b32_e32 v132, 16, v2
	v_lshlrev_b32_e32 v136, 16, v3
	v_and_b32_e32 v133, 0xffff0000, v2
	v_and_b32_e32 v137, 0xffff0000, v3
	v_lshlrev_b32_e32 v116, 16, v4
	v_lshlrev_b32_e32 v118, 16, v5
	v_and_b32_e32 v117, 0xffff0000, v4
	v_and_b32_e32 v119, 0xffff0000, v5
	v_and_b32_e32 v145, 0xffff0000, v27
	v_lshlrev_b32_e32 v112, 16, v8
	v_lshlrev_b32_e32 v114, 16, v9
	v_and_b32_e32 v113, 0xffff0000, v8
	v_and_b32_e32 v115, 0xffff0000, v9
	v_lshlrev_b32_e32 v130, 16, v6
	v_lshlrev_b32_e32 v134, 16, v7
	v_and_b32_e32 v131, 0xffff0000, v6
	v_and_b32_e32 v135, 0xffff0000, v7
	v_and_b32_e32 v125, 0xffff0000, v30
	v_lshlrev_b32_e32 v142, 16, v11
	v_lshlrev_b32_e32 v144, 16, v10
	v_lshlrev_b32_e32 v124, 16, v13
	v_lshlrev_b32_e32 v126, 16, v12
	v_and_b32_e32 v127, 0xffff0000, v28
	v_lshlrev_b32_e32 v28, 16, v19
	v_and_b32_e32 v19, 0xffff0000, v31
	v_lshlrev_b32_e32 v138, 16, v14
	v_lshlrev_b32_e32 v140, 16, v15
	v_lshlrev_b32_e32 v120, 16, v16
	v_lshlrev_b32_e32 v122, 16, v17
	v_and_b32_e32 v139, 0xffff0000, v1
	ds_read_b32 v1, v161
	v_and_b32_e32 v143, 0xffff0000, v29
	v_and_b32_e32 v29, 0xffff0000, v32
	v_and_b32_e32 v149, 0xffff0000, v33
	v_lshlrev_b32_e32 v18, 16, v18
	v_lshlrev_b32_e32 v148, 16, v20
	v_lshlrev_b32_e32 v150, 16, v21
	s_waitcnt lgkmcnt(0)
	v_mul_f32_e32 v1, 0x3fb8aa3b, v1
	v_exp_f32_e32 v106, v1
	v_and_b32_e32 v151, 0xffff0000, v89
	v_lshl_add_u64 v[104:105], v[46:47], 1, v[102:103]
	ds_read_b128 v[2:5], v233
	ds_read_b128 v[6:9], v233 offset:512
	ds_read_b128 v[10:13], v233 offset:1024
	ds_read_b128 v[14:17], v233 offset:1536
	s_waitcnt vmcnt(0) lgkmcnt(0)
	v_pk_fma_f32 v[32:33], v[2:3], v[132:133], 0 op_sel_hi:[1,1,0]
	v_pk_fma_f32 v[20:21], v[4:5], v[136:137], 0 op_sel_hi:[1,1,0]
	v_pk_fma_f32 v[2:3], v[2:3], v[130:131], 0 op_sel_hi:[1,1,0]
	v_pk_fma_f32 v[4:5], v[4:5], v[134:135], 0 op_sel_hi:[1,1,0]
	v_pk_fma_f32 v[32:33], v[6:7], v[138:139], v[32:33]
	v_pk_fma_f32 v[20:21], v[8:9], v[140:141], v[20:21]
	v_pk_fma_f32 v[2:3], v[6:7], v[132:133], v[2:3]
	v_pk_fma_f32 v[4:5], v[8:9], v[136:137], v[4:5]
	v_pk_fma_f32 v[32:33], v[10:11], v[144:145], v[32:33]
	v_pk_fma_f32 v[20:21], v[12:13], v[142:143], v[20:21]
	v_pk_fma_f32 v[2:3], v[10:11], v[138:139], v[2:3]
	v_pk_fma_f32 v[18:19], v[14:15], v[18:19], v[32:33]
	v_pk_fma_f32 v[20:21], v[16:17], v[28:29], v[20:21]
	v_mul_f32_e32 v1, 0xbfb8aa3b, v18
	v_exp_f32_e32 v28, v1
	v_mul_f32_e32 v1, 0xbfb8aa3b, v19
	v_exp_f32_e32 v29, v1
	v_mul_f32_e32 v1, 0xbfb8aa3b, v20
	v_exp_f32_e32 v32, v1
	v_mul_f32_e32 v1, 0xbfb8aa3b, v21
	v_exp_f32_e32 v33, v1
	v_pk_add_f32 v[28:29], v[28:29], 1.0 op_sel_hi:[1,0]
	v_pk_fma_f32 v[2:3], v[14:15], v[144:145], v[2:3]
	v_pk_fma_f32 v[4:5], v[12:13], v[140:141], v[4:5]
	v_pk_add_f32 v[32:33], v[32:33], 1.0 op_sel_hi:[1,0]
	v_pk_fma_f32 v[4:5], v[16:17], v[142:143], v[4:5]
	v_div_scale_f32 v1, s[8:9], v33, v33, 1.0
	v_rcp_f32_e32 v85, v1
	s_nop 0
	v_fma_f32 v89, -v1, v85, 1.0
	v_fmac_f32_e32 v85, v89, v85
	v_div_scale_f32 v89, vcc, 1.0, v33, 1.0
	v_mul_f32_e32 v91, v89, v85
	v_fma_f32 v93, -v1, v91, v89
	v_fmac_f32_e32 v91, v93, v85
	v_fma_f32 v1, -v1, v91, v89
	v_div_fmas_f32 v1, v1, v85, v91
	v_div_fixup_f32 v33, v1, v33, 1.0
	v_div_scale_f32 v1, s[8:9], v32, v32, 1.0
	v_rcp_f32_e32 v85, v1
	s_nop 0
	v_fma_f32 v89, -v1, v85, 1.0
	v_fmac_f32_e32 v85, v89, v85
	v_div_scale_f32 v89, vcc, 1.0, v32, 1.0
	v_mul_f32_e32 v91, v89, v85
	v_fma_f32 v93, -v1, v91, v89
	v_fmac_f32_e32 v91, v93, v85
	v_fma_f32 v1, -v1, v91, v89
	v_div_fmas_f32 v1, v1, v85, v91
	v_div_fixup_f32 v32, v1, v32, 1.0
	v_div_scale_f32 v1, s[8:9], v29, v29, 1.0
	v_rcp_f32_e32 v85, v1
	v_pk_mul_f32 v[110:111], v[20:21], v[32:33]
	v_fma_f32 v89, -v1, v85, 1.0
	v_fmac_f32_e32 v85, v89, v85
	v_div_scale_f32 v89, vcc, 1.0, v29, 1.0
	v_mul_f32_e32 v91, v89, v85
	v_fma_f32 v93, -v1, v91, v89
	v_fmac_f32_e32 v91, v93, v85
	v_fma_f32 v1, -v1, v91, v89
	v_div_fmas_f32 v1, v1, v85, v91
	v_div_fixup_f32 v29, v1, v29, 1.0
	v_div_scale_f32 v1, s[8:9], v28, v28, 1.0
	v_rcp_f32_e32 v85, v1
	v_pk_mul_f32 v[128:129], v[110:111], v[110:111]
	v_fma_f32 v89, -v1, v85, 1.0
	v_fmac_f32_e32 v85, v89, v85
	v_div_scale_f32 v89, vcc, 1.0, v28, 1.0
	v_mul_f32_e32 v91, v89, v85
	v_fma_f32 v93, -v1, v91, v89
	v_fmac_f32_e32 v91, v93, v85
	v_fma_f32 v1, -v1, v91, v89
	v_div_fmas_f32 v1, v1, v85, v91
	v_div_fixup_f32 v28, v1, v28, 1.0
	v_pk_mul_f32 v[108:109], v[18:19], v[28:29]
	ds_read_b128 v[18:21], v233 offset:16
	ds_read_b128 v[22:25], v233 offset:528
	ds_read_b128 v[26:29], v233 offset:1040
	ds_read_b128 v[30:33], v233 offset:1552
	v_pk_mul_f32 v[146:147], v[108:109], v[108:109]
	s_waitcnt vmcnt(0) lgkmcnt(0)
; __device__ __forceinline__ float bflo(unsigned w) { return __uint_as_float(w << 16); }
; __device__ __forceinline__ float bfhi(unsigned w) { return __uint_as_float(w & 0xffff0000u); }
; __device__ __forceinline__ float sigmoidf_(float x) { return __frcp_rn(1.f + __expf(-x)); }
; __device__ __forceinline__ void prepB(const Params& p, int h, int n, char* shmc, int tid, int wv) {
;     ...
;       float out[2][8];
; #pragma unroll
;       for (int tt = 0; tt < 2; ++tt)
; #pragma unroll
;         for (int i = 0; i < 8; ++i) out[tt][i] = 0.f;
; #pragma unroll
;       for (int rr = 0; rr < 5; ++rr) {
;         const uint4 raw = rawv[rr];
;         const unsigned rw[4] = {raw.x, raw.y, raw.z, raw.w};
;         float xv[8];
; #pragma unroll
;         for (int i = 0; i < 4; ++i) { xv[2 * i] = bflo(rw[i]); xv[2 * i + 1] = bfhi(rw[i]); }
; #pragma unroll
;         for (int tt = 0; tt < 2; ++tt) {
;           const int j = rr - tt;
;           if (j >= 0 && j < 4) {
; #pragma unroll
;             for (int i = 0; i < 8; ++i) out[tt][i] += w[j][i] * xv[i];
;           }
;         }
;       }
; #pragma unroll
;       for (int tt = 0; tt < 2; ++tt) {
;         const int t = t0 + tt;
;         float ss = 0.f;
; #pragma unroll
;         for (int i = 0; i < 8; ++i) { const float o = out[tt][i]; out[tt][i] = o * sigmoidf_(o); ss += out[tt][i] * out[tt][i]; }
	v_pk_fma_f32 v[154:155], v[18:19], v[116:117], 0 op_sel_hi:[1,1,0]
	s_nop 0
	v_pk_fma_f32 v[154:155], v[22:23], v[120:121], v[154:155]
	v_pk_fma_f32 v[152:153], v[20:21], v[118:119], 0 op_sel_hi:[1,1,0]
	v_pk_fma_f32 v[154:155], v[26:27], v[126:127], v[154:155]
	v_pk_fma_f32 v[152:153], v[24:25], v[122:123], v[152:153]
	v_pk_fma_f32 v[148:149], v[30:31], v[148:149], v[154:155]
	v_pk_fma_f32 v[152:153], v[28:29], v[124:125], v[152:153]
	v_mul_f32_e32 v1, 0xbfb8aa3b, v148
	v_pk_fma_f32 v[150:151], v[32:33], v[150:151], v[152:153]
	v_exp_f32_e32 v152, v1
	v_mul_f32_e32 v1, 0xbfb8aa3b, v149
	v_exp_f32_e32 v153, v1
	v_mul_f32_e32 v1, 0xbfb8aa3b, v150
	v_exp_f32_e32 v154, v1
	v_mul_f32_e32 v1, 0xbfb8aa3b, v151
	v_exp_f32_e32 v155, v1
	v_pk_add_f32 v[152:153], v[152:153], 1.0 op_sel_hi:[1,0]
	v_pk_add_f32 v[154:155], v[154:155], 1.0 op_sel_hi:[1,0]
	s_nop 0
	v_div_scale_f32 v1, s[8:9], v155, v155, 1.0
	v_rcp_f32_e32 v85, v1
	s_nop 0
	v_fma_f32 v89, -v1, v85, 1.0
	v_fmac_f32_e32 v85, v89, v85
	v_div_scale_f32 v89, vcc, 1.0, v155, 1.0
	v_mul_f32_e32 v91, v89, v85
	v_fma_f32 v93, -v1, v91, v89
	v_fmac_f32_e32 v91, v93, v85
	v_fma_f32 v1, -v1, v91, v89
	v_div_fmas_f32 v1, v1, v85, v91
	v_div_fixup_f32 v155, v1, v155, 1.0
	v_div_scale_f32 v1, s[8:9], v154, v154, 1.0
	v_rcp_f32_e32 v85, v1
	s_nop 0
	v_fma_f32 v89, -v1, v85, 1.0
	v_fmac_f32_e32 v85, v89, v85
	v_div_scale_f32 v89, vcc, 1.0, v154, 1.0
	v_mul_f32_e32 v91, v89, v85
	v_fma_f32 v93, -v1, v91, v89
	v_fmac_f32_e32 v91, v93, v85
	v_fma_f32 v1, -v1, v91, v89
	v_div_fmas_f32 v1, v1, v85, v91
	v_div_fixup_f32 v154, v1, v154, 1.0
	v_div_scale_f32 v1, s[8:9], v153, v153, 1.0
	v_rcp_f32_e32 v85, v1
	v_pk_mul_f32 v[150:151], v[150:151], v[154:155]
	v_fma_f32 v89, -v1, v85, 1.0
	v_fmac_f32_e32 v85, v89, v85
	v_div_scale_f32 v89, vcc, 1.0, v153, 1.0
	v_mul_f32_e32 v91, v89, v85
	v_fma_f32 v93, -v1, v91, v89
	v_fmac_f32_e32 v91, v93, v85
	v_fma_f32 v1, -v1, v91, v89
	v_div_fmas_f32 v1, v1, v85, v91
	v_div_fixup_f32 v153, v1, v153, 1.0
	v_div_scale_f32 v1, s[8:9], v152, v152, 1.0
	v_rcp_f32_e32 v85, v1
	s_nop 0
	v_fma_f32 v89, -v1, v85, 1.0
	v_fmac_f32_e32 v85, v89, v85
	v_div_scale_f32 v89, vcc, 1.0, v152, 1.0
	v_mul_f32_e32 v91, v89, v85
	v_fma_f32 v93, -v1, v91, v89
	v_fmac_f32_e32 v91, v93, v85
	v_fma_f32 v1, -v1, v91, v89
	v_div_fmas_f32 v1, v1, v85, v91
	v_div_fixup_f32 v152, v1, v152, 1.0
	v_mul_f32_e32 v1, 0xbfb8aa3b, v2
	v_exp_f32_e32 v6, v1
	v_mul_f32_e32 v1, 0xbfb8aa3b, v3
	v_exp_f32_e32 v7, v1
	v_mul_f32_e32 v1, 0xbfb8aa3b, v4
	v_exp_f32_e32 v8, v1
	v_mul_f32_e32 v1, 0xbfb8aa3b, v5
	v_exp_f32_e32 v9, v1
	v_pk_add_f32 v[6:7], v[6:7], 1.0 op_sel_hi:[1,0]
	v_pk_mul_f32 v[148:149], v[148:149], v[152:153]
	v_pk_mul_f32 v[152:153], v[150:151], v[150:151]
	v_pk_add_f32 v[8:9], v[8:9], 1.0 op_sel_hi:[1,0]
	v_pk_mul_f32 v[154:155], v[148:149], v[148:149]
	v_div_scale_f32 v1, s[8:9], v9, v9, 1.0
	v_rcp_f32_e32 v10, v1
	s_nop 0
	v_fma_f32 v11, -v1, v10, 1.0
	v_fmac_f32_e32 v10, v11, v10
	v_div_scale_f32 v11, vcc, 1.0, v9, 1.0
	v_mul_f32_e32 v12, v11, v10
	v_fma_f32 v13, -v1, v12, v11
	v_fmac_f32_e32 v12, v13, v10
	v_fma_f32 v1, -v1, v12, v11
	v_div_fmas_f32 v1, v1, v10, v12
	v_div_fixup_f32 v9, v1, v9, 1.0
	v_div_scale_f32 v1, s[8:9], v8, v8, 1.0
	v_rcp_f32_e32 v10, v1
	s_nop 0
	v_fma_f32 v11, -v1, v10, 1.0
	v_fmac_f32_e32 v10, v11, v10
	v_div_scale_f32 v11, vcc, 1.0, v8, 1.0
	v_mul_f32_e32 v12, v11, v10
	v_fma_f32 v13, -v1, v12, v11
	v_fmac_f32_e32 v12, v13, v10
	v_fma_f32 v1, -v1, v12, v11
	v_div_fmas_f32 v1, v1, v10, v12
	v_div_fixup_f32 v8, v1, v8, 1.0
	v_div_scale_f32 v1, s[8:9], v7, v7, 1.0
	v_rcp_f32_e32 v10, v1
	v_pk_mul_f32 v[4:5], v[4:5], v[8:9]
	v_fma_f32 v11, -v1, v10, 1.0
	v_fmac_f32_e32 v10, v11, v10
	v_div_scale_f32 v11, vcc, 1.0, v7, 1.0
	v_mul_f32_e32 v12, v11, v10
	v_fma_f32 v13, -v1, v12, v11
	v_fmac_f32_e32 v12, v13, v10
	v_fma_f32 v1, -v1, v12, v11
	v_div_fmas_f32 v1, v1, v10, v12
	v_div_fixup_f32 v7, v1, v7, 1.0
	v_div_scale_f32 v1, s[8:9], v6, v6, 1.0
	v_rcp_f32_e32 v10, v1
	s_nop 0
	v_fma_f32 v11, -v1, v10, 1.0
	v_fmac_f32_e32 v10, v11, v10
	v_div_scale_f32 v11, vcc, 1.0, v6, 1.0
	v_mul_f32_e32 v12, v11, v10
	v_fma_f32 v13, -v1, v12, v11
	v_fmac_f32_e32 v12, v13, v10
	v_fma_f32 v1, -v1, v12, v11
	v_div_fmas_f32 v1, v1, v10, v12
	v_div_fixup_f32 v6, v1, v6, 1.0
	v_pk_mul_f32 v[2:3], v[2:3], v[6:7]
	v_pk_fma_f32 v[12:13], v[18:19], v[112:113], 0 op_sel_hi:[1,1,0]
	v_pk_mul_f32 v[8:9], v[2:3], v[2:3]
	v_mov_b32_e32 v10, v146
	v_mov_b32_e32 v11, v8
	v_mov_b32_e32 v8, v147
	v_pk_fma_f32 v[12:13], v[22:23], v[116:117], v[12:13]
	v_pk_add_f32 v[8:9], v[10:11], v[8:9]
	v_pk_fma_f32 v[10:11], v[20:21], v[114:115], 0 op_sel_hi:[1,1,0]
	v_pk_fma_f32 v[12:13], v[26:27], v[120:121], v[12:13]
	v_pk_fma_f32 v[10:11], v[24:25], v[118:119], v[10:11]
	v_pk_fma_f32 v[12:13], v[30:31], v[126:127], v[12:13]
	v_pk_fma_f32 v[10:11], v[28:29], v[122:123], v[10:11]
	v_mul_f32_e32 v1, 0xbfb8aa3b, v12
	v_pk_fma_f32 v[10:11], v[32:33], v[124:125], v[10:11]
	v_exp_f32_e32 v14, v1
	v_mul_f32_e32 v1, 0xbfb8aa3b, v13
	v_exp_f32_e32 v15, v1
	v_mul_f32_e32 v1, 0xbfb8aa3b, v10
	v_exp_f32_e32 v16, v1
	v_mul_f32_e32 v1, 0xbfb8aa3b, v11
	v_exp_f32_e32 v17, v1
	v_pk_add_f32 v[14:15], v[14:15], 1.0 op_sel_hi:[1,0]
	v_pk_mul_f32 v[6:7], v[4:5], v[4:5]
	v_mov_b32_e32 v22, 0
	v_pk_add_f32 v[16:17], v[16:17], 1.0 op_sel_hi:[1,0]
	v_mov_b32_e32 v23, 0
	v_div_scale_f32 v1, s[8:9], v17, v17, 1.0
	v_rcp_f32_e32 v18, v1
	v_mov_b32_e32 v24, 0
	v_mov_b32_e32 v25, 0
	v_fma_f32 v19, -v1, v18, 1.0
	v_fmac_f32_e32 v18, v19, v18
; __device__ __forceinline__ unsigned pack2(float a, float b) { const f32v2_ v = {a, b}; const bf16v2_ r = __builtin_convertvector(v, bf16v2_); return __builtin_bit_cast(unsigned, r); }
; __device__ __forceinline__ float shfl_idx(float v, int srclane) { return __int_as_float(__builtin_amdgcn_ds_bpermute(srclane << 2, __float_as_int(v))); }
; __device__ __forceinline__ int perm32(int c) { return ((c >> 2) & 3) * 8 + ((c >> 4) & 1) * 4 + (c & 3); }
; __device__ __forceinline__ void prepB(const Params& p, int h, int n, char* shmc, int tid, int wv) {
;     ...
;         if (sig < 2) {
; #pragma unroll
;           for (int o = 1; o < 16; o <<= 1) ss += shfl_idx(ss, (tid & 63) ^ o);
;           const float rs = rsqrtf(ss + EPS_);
;           if (sig == 0) {
;             const float eg = __expf(gcS[t]);
;             float qn[8];
; #pragma unroll
;             for (int i = 0; i < 8; ++i) { qn[i] = out[tt][i] * rs * 0.08838834764831845f; qB[t * 136 + c0 + i] = f2bf(qn[i]); }
;             u16* qd = QPB + (long)tix * 8192;
; #pragma unroll
;             for (int g = 0; g < 2; ++g) {
;               uint2 o; o.x = pack2(qn[4 * g] * eg, qn[4 * g + 1] * eg); o.y = pack2(qn[4 * g + 2] * eg, qn[4 * g + 3] * eg);
;               const int p0 = (c0 & ~31) + perm32((c0 & 31) + 4 * g);
;               *(uint2*)(qd + ((((t >> 4) * 4 + (p0 >> 5)) * 64 + ((p0 >> 3) & 3) * 16 + (t & 15)) * 8) + (p0 & 7)) = o;
;             }
	v_div_scale_f32 v19, vcc, 1.0, v17, 1.0
	v_mul_f32_e32 v20, v19, v18
	v_fma_f32 v21, -v1, v20, v19
	v_fmac_f32_e32 v20, v21, v18
	v_fma_f32 v1, -v1, v20, v19
	v_div_fmas_f32 v1, v1, v18, v20
	v_div_fixup_f32 v17, v1, v17, 1.0
	v_div_scale_f32 v1, s[8:9], v16, v16, 1.0
	v_rcp_f32_e32 v18, v1
	s_nop 0
	v_fma_f32 v19, -v1, v18, 1.0
	v_fmac_f32_e32 v18, v19, v18
	v_div_scale_f32 v19, vcc, 1.0, v16, 1.0
	v_mul_f32_e32 v20, v19, v18
	v_fma_f32 v21, -v1, v20, v19
	v_fmac_f32_e32 v20, v21, v18
	v_fma_f32 v1, -v1, v20, v19
	v_div_fmas_f32 v1, v1, v18, v20
	v_div_fixup_f32 v16, v1, v16, 1.0
	v_div_scale_f32 v1, s[8:9], v15, v15, 1.0
	v_rcp_f32_e32 v18, v1
	v_pk_mul_f32 v[10:11], v[10:11], v[16:17]
	v_fma_f32 v19, -v1, v18, 1.0
	v_fmac_f32_e32 v18, v19, v18
	v_div_scale_f32 v19, vcc, 1.0, v15, 1.0
	v_mul_f32_e32 v20, v19, v18
	v_fma_f32 v21, -v1, v20, v19
	v_fmac_f32_e32 v20, v21, v18
	v_fma_f32 v1, -v1, v20, v19
	v_div_fmas_f32 v1, v1, v18, v20
	v_div_fixup_f32 v15, v1, v15, 1.0
	v_div_scale_f32 v1, s[8:9], v14, v14, 1.0
	v_rcp_f32_e32 v18, v1
	s_mov_b32 s8, 0x358637bd
	v_fma_f32 v19, -v1, v18, 1.0
	v_fmac_f32_e32 v18, v19, v18
	v_div_scale_f32 v19, vcc, 1.0, v14, 1.0
	v_mul_f32_e32 v20, v19, v18
	v_fma_f32 v21, -v1, v20, v19
	v_fmac_f32_e32 v20, v21, v18
	v_fma_f32 v1, -v1, v20, v19
	v_div_fmas_f32 v1, v1, v18, v20
	v_div_fixup_f32 v14, v1, v14, 1.0
	v_pk_mul_f32 v[12:13], v[12:13], v[14:15]
	v_mov_b32_e32 v18, v128
	v_mov_b32_e32 v19, v6
	v_pk_mul_f32 v[16:17], v[12:13], v[12:13]
	v_pk_add_f32 v[8:9], v[8:9], v[18:19]
	v_mov_b32_e32 v6, v129
	v_pk_add_f32 v[6:7], v[8:9], v[6:7]
	v_mov_b32_e32 v8, v154
	v_mov_b32_e32 v9, v16
	v_pk_mul_f32 v[14:15], v[10:11], v[10:11]
	v_pk_add_f32 v[6:7], v[6:7], v[8:9]
	v_mov_b32_e32 v16, v155
	v_pk_add_f32 v[6:7], v[6:7], v[16:17]
	v_mov_b32_e32 v8, v152
	v_mov_b32_e32 v9, v14
	v_pk_add_f32 v[6:7], v[6:7], v[8:9]
	v_mov_b32_e32 v14, v153
	v_pk_add_f32 v[6:7], v[6:7], v[14:15]
	ds_bpermute_b32 v9, v157, v7
	ds_bpermute_b32 v8, v157, v6
	v_or_b32_e32 v20, 0x400, v87
	s_waitcnt lgkmcnt(0)
	v_pk_add_f32 v[6:7], v[6:7], v[8:9]
	ds_bpermute_b32 v9, v158, v7
	ds_bpermute_b32 v8, v158, v6
	s_waitcnt lgkmcnt(0)
	v_pk_add_f32 v[6:7], v[6:7], v[8:9]
	ds_bpermute_b32 v9, v159, v7
	ds_bpermute_b32 v8, v159, v6
	s_waitcnt lgkmcnt(0)
	v_pk_add_f32 v[6:7], v[6:7], v[8:9]
	ds_bpermute_b32 v9, v160, v7
	ds_bpermute_b32 v8, v160, v6
	s_waitcnt lgkmcnt(0)
	v_pk_add_f32 v[6:7], v[6:7], v[8:9]
	s_nop 0
	v_pk_add_f32 v[6:7], v[6:7], s[8:9] op_sel_hi:[1,0]
	s_nop 0
	v_mul_f32_e32 v1, 0x4b800000, v7
	v_cmp_gt_f32_e64 s[86:87], s70, v7
	v_cmp_gt_f32_e32 vcc, s70, v6
	s_nop 0
	v_cndmask_b32_e64 v1, v7, v1, s[86:87]
	v_rsq_f32_e32 v1, v1
	s_nop 0
	v_mul_f32_e32 v7, 0x45800000, v1
	v_cndmask_b32_e64 v8, v1, v7, s[86:87]
	v_pk_mul_f32 v[2:3], v[2:3], v[8:9] op_sel_hi:[1,0]
	v_pk_mul_f32 v[4:5], v[4:5], v[8:9] op_sel_hi:[1,0]
	v_pk_mul_f32 v[16:17], v[2:3], s[56:57] op_sel_hi:[1,0]
	v_pk_mul_f32 v[14:15], v[4:5], s[56:57] op_sel_hi:[1,0]
	v_pk_mul_f32 v[2:3], v[12:13], v[8:9] op_sel_hi:[1,0]
	v_pk_mul_f32 v[4:5], v[10:11], v[8:9] op_sel_hi:[1,0]
	v_pk_mul_f32 v[10:11], v[2:3], s[56:57] op_sel_hi:[1,0]
	v_pk_mul_f32 v[8:9], v[4:5], s[56:57] op_sel_hi:[1,0]
	v_add_u32_e32 v1, v156, v162
	v_cvt_pk_bf16_f32 v5, v8, v9
	v_cvt_pk_bf16_f32 v4, v10, v11
	v_cvt_pk_bf16_f32 v3, v14, v15
	v_cvt_pk_bf16_f32 v2, v16, v17
	ds_write_b128 v1, v[2:5]
	v_mul_f32_e32 v1, 0x4b800000, v6
	v_cndmask_b32_e32 v1, v6, v1, vcc
	v_pk_mul_f32 v[2:3], v[106:107], v[16:17] op_sel_hi:[0,1]
	v_pk_mul_f32 v[4:5], v[106:107], v[14:15] op_sel_hi:[0,1]
	v_rsq_f32_e32 v1, v1
	v_cvt_pk_bf16_f32 v2, v2, v3
	v_cvt_pk_bf16_f32 v3, v4, v5
	flat_store_dwordx2 v[104:105], v[2:3]
	v_pk_mul_f32 v[2:3], v[106:107], v[10:11] op_sel_hi:[0,1]
	v_pk_mul_f32 v[4:5], v[106:107], v[8:9] op_sel_hi:[0,1]
	v_cvt_pk_bf16_f32 v2, v2, v3
	v_cvt_pk_bf16_f32 v3, v4, v5
	flat_store_dwordx2 v[104:105], v[2:3] offset:256
	v_mul_f32_e32 v2, 0x45800000, v1
	v_cndmask_b32_e32 v2, v1, v2, vcc
	ds_read_b32 v1, v163
	v_pk_mul_f32 v[4:5], v[108:109], v[2:3] op_sel_hi:[1,0]
	v_pk_mul_f32 v[6:7], v[110:111], v[2:3] op_sel_hi:[1,0]
	v_pk_mul_f32 v[8:9], v[4:5], s[56:57] op_sel_hi:[1,0]
	v_pk_mul_f32 v[4:5], v[148:149], v[2:3] op_sel_hi:[1,0]
	v_pk_mul_f32 v[2:3], v[150:151], v[2:3] op_sel_hi:[1,0]
	v_pk_mul_f32 v[6:7], v[6:7], s[56:57] op_sel_hi:[1,0]
	v_pk_mul_f32 v[10:11], v[2:3], s[56:57] op_sel_hi:[1,0]
	v_pk_mul_f32 v[12:13], v[4:5], s[56:57] op_sel_hi:[1,0]
	s_waitcnt lgkmcnt(0)
	v_mul_f32_e32 v1, 0x3fb8aa3b, v1
	v_add_u32_e32 v14, v156, v164
	v_cvt_pk_bf16_f32 v5, v10, v11
	v_cvt_pk_bf16_f32 v4, v12, v13
	v_cvt_pk_bf16_f32 v3, v6, v7
	v_cvt_pk_bf16_f32 v2, v8, v9
	ds_write_b128 v14, v[2:5]
	v_exp_f32_e32 v2, v1
	v_mov_b32_e32 v1, 0
	v_pk_mul_f32 v[4:5], v[2:3], v[8:9] op_sel_hi:[0,1]
	v_pk_mul_f32 v[6:7], v[2:3], v[6:7] op_sel_hi:[0,1]
	v_cvt_pk_bf16_f32 v4, v4, v5
	v_cvt_pk_bf16_f32 v5, v6, v7
	v_lshl_add_u64 v[6:7], v[48:49], 1, v[102:103]
	flat_store_dwordx2 v[6:7], v[4:5]
	v_pk_mul_f32 v[4:5], v[2:3], v[12:13] op_sel_hi:[0,1]
	v_pk_mul_f32 v[2:3], v[2:3], v[10:11] op_sel_hi:[0,1]
	v_cvt_pk_bf16_f32 v4, v4, v5
	v_cvt_pk_bf16_f32 v5, v2, v3
	v_mov_b32_e32 v2, 0
	v_mov_b32_e32 v3, 0
	flat_store_dwordx2 v[6:7], v[4:5] offset:256
	s_and_saveexec_b64 s[86:87], s[76:77]
	s_cbranch_execz .LBB0_448
	v_mad_u64_u32 v[0:1], s[8:9], v34, s42, v[36:37]
	v_mad_i32_i24 v1, v35, s42, v1
	v_lshlrev_b32_e32 v212, 1, v20
	v_lshl_add_u64 v[0:1], v[0:1], 0, v[212:213]
	global_load_dwordx4 v[0:3], v[0:1], off

; __device__ __forceinline__ float bflo(unsigned w) { return __uint_as_float(w << 16); }
; __device__ __forceinline__ float bfhi(unsigned w) { return __uint_as_float(w & 0xffff0000u); }
; __device__ __forceinline__ uint4 ldg16(const void* p) { const u32x4 v = *(const __attribute__((address_space(1))) u32x4*)(p); return make_uint4(v.x, v.y, v.z, v.w); }
; __device__ __forceinline__ float sigmoidf_(float x) { return __frcp_rn(1.f + __expf(-x)); }
; __device__ __forceinline__ void prepB(const Params& p, int h, int n, char* shmc, int tid, int wv) {
;     ...
;       const int colg = sig * 1024 + h * 128 + c0;
;       uint4 rawv[5];
; #pragma unroll
;       for (int rr = 0; rr < 5; ++rr) {
;         const long tok = rowbase + t0 - 3 + rr;
;         rawv[rr] = make_uint4(0u, 0u, 0u, 0u);
;         if (tok >= 0) rawv[rr] = ldg16(GQKV + tok * 3072 + colg);
;       }
;       float w[4][8];
; #pragma unroll
;       for (int j = 0; j < 4; ++j) {
;         const float4 wa = *(const float4*)(p.a_conv_w + j * 3072 + colg), wb = *(const float4*)(p.a_conv_w + j * 3072 + colg + 4);
;         w[j][0] = wa.x; w[j][1] = wa.y; w[j][2] = wa.z; w[j][3] = wa.w; w[j][4] = wb.x; w[j][5] = wb.y; w[j][6] = wb.z; w[j][7] = wb.w;
;       }
;       float out[2][8];
; #pragma unroll
;       for (int tt = 0; tt < 2; ++tt)
; #pragma unroll
;         for (int i = 0; i < 8; ++i) out[tt][i] = 0.f;
; #pragma unroll
;       for (int rr = 0; rr < 5; ++rr) {
;         const uint4 raw = rawv[rr];
;         const unsigned rw[4] = {raw.x, raw.y, raw.z, raw.w};
;         float xv[8];
; #pragma unroll
;         for (int i = 0; i < 4; ++i) { xv[2 * i] = bflo(rw[i]); xv[2 * i + 1] = bfhi(rw[i]); }
; #pragma unroll
;         for (int tt = 0; tt < 2; ++tt) {
;           const int j = rr - tt;
;           if (j >= 0 && j < 4) {
; #pragma unroll
;             for (int i = 0; i < 8; ++i) out[tt][i] += w[j][i] * xv[i];
;           }
;         }
;       }
; #pragma unroll
;       for (int tt = 0; tt < 2; ++tt) {
;         const int t = t0 + tt;
;         float ss = 0.f;
; #pragma unroll
;         for (int i = 0; i < 8; ++i) { const float o = out[tt][i]; out[tt][i] = o * sigmoidf_(o); ss += out[tt][i] * out[tt][i]; }
.LBB0_456:
	s_or_b64 exec, exec, s[86:87]
	s_waitcnt vmcnt(0)
	s_mov_b64 s[86:87], exec
	s_and_b64 exec, s[86:87], s[76:77]
	v_mov_b32_e32 v22, v0
	v_mov_b32_e32 v23, v1
	v_mov_b32_e32 v24, v2
	v_mov_b32_e32 v25, v3
	s_and_b64 exec, s[86:87], s[78:79]
	v_mov_b32_e32 v26, v8
	v_mov_b32_e32 v27, v9
	v_mov_b32_e32 v28, v10
	v_mov_b32_e32 v29, v11
	s_and_b64 exec, s[86:87], s[80:81]
	v_mov_b32_e32 v30, v4
	v_mov_b32_e32 v31, v5
	v_mov_b32_e32 v85, v6
	v_mov_b32_e32 v89, v7
	s_and_b64 exec, s[86:87], s[82:83]
	v_mov_b32_e32 v91, v16
	v_mov_b32_e32 v102, v17
	v_mov_b32_e32 v93, v18
	v_mov_b32_e32 v103, v19
	s_and_b64 exec, s[86:87], s[84:85]
	v_mov_b32_e32 v104, v12
	v_mov_b32_e32 v105, v13
	v_mov_b32_e32 v122, v14
	v_mov_b32_e32 v123, v15
	s_mov_b64 exec, s[86:87]
	v_lshlrev_b32_e32 v212, 2, v20
	v_and_b32_e32 v125, 0xffff0000, v22
	v_and_b32_e32 v129, 0xffff0000, v23
	v_and_b32_e32 v107, 0xffff0000, v24
	v_lshlrev_b32_e32 v106, 16, v2
	v_lshlrev_b32_e32 v108, 16, v3
	v_and_b32_e32 v109, 0xffff0000, v25
	v_lshlrev_b32_e32 v124, 16, v0
	v_lshlrev_b32_e32 v128, 16, v1
	v_and_b32_e32 v111, 0xffff0000, v28
	v_lshlrev_b32_e32 v132, 16, v4
	v_lshlrev_b32_e32 v134, 16, v5
	v_lshlrev_b32_e32 v114, 16, v6
	v_lshlrev_b32_e32 v116, 16, v7
	v_lshlrev_b32_e32 v126, 16, v8
	v_lshlrev_b32_e32 v130, 16, v9
	v_lshlrev_b32_e32 v110, 16, v10
	v_lshlrev_b32_e32 v112, 16, v11
	v_and_b32_e32 v113, 0xffff0000, v29
	v_lshlrev_b32_e32 v138, 16, v16
	v_lshlrev_b32_e32 v120, 16, v18
	v_lshlrev_b32_e32 v16, 16, v12
	v_lshlrev_b32_e32 v18, 16, v13
	v_lshlrev_b32_e32 v142, 16, v14
	v_lshlrev_b32_e32 v144, 16, v15
	v_and_b32_e32 v131, 0xffff0000, v27
	v_and_b32_e32 v127, 0xffff0000, v26
	v_and_b32_e32 v135, 0xffff0000, v31
	v_and_b32_e32 v133, 0xffff0000, v30
	v_lshlrev_b32_e32 v136, 16, v17
	v_and_b32_e32 v137, 0xffff0000, v102
	v_and_b32_e32 v139, 0xffff0000, v91
	v_lshlrev_b32_e32 v118, 16, v19
	v_and_b32_e32 v19, 0xffff0000, v105
	v_and_b32_e32 v17, 0xffff0000, v104
	v_and_b32_e32 v115, 0xffff0000, v85
	v_and_b32_e32 v117, 0xffff0000, v89
	v_and_b32_e32 v121, 0xffff0000, v93
	v_and_b32_e32 v119, 0xffff0000, v103
	v_and_b32_e32 v143, 0xffff0000, v122
	v_and_b32_e32 v145, 0xffff0000, v123
	s_waitcnt vmcnt(0) lgkmcnt(0)
	ds_read_b128 v[0:3], v233 offset:2048
	ds_read_b128 v[4:7], v233 offset:2560
	ds_read_b128 v[8:11], v233 offset:3072
	ds_read_b128 v[12:15], v233 offset:3584
	s_waitcnt vmcnt(0) lgkmcnt(0)
	v_pk_fma_f32 v[26:27], v[2:3], v[130:131], 0 op_sel_hi:[1,1,0]
	v_pk_fma_f32 v[30:31], v[0:1], v[126:127], 0 op_sel_hi:[1,1,0]
	v_pk_fma_f32 v[2:3], v[2:3], v[128:129], 0 op_sel_hi:[1,1,0]
	v_pk_fma_f32 v[0:1], v[0:1], v[124:125], 0 op_sel_hi:[1,1,0]
	v_pk_fma_f32 v[26:27], v[6:7], v[134:135], v[26:27]
	v_pk_fma_f32 v[30:31], v[4:5], v[132:133], v[30:31]
	v_pk_fma_f32 v[2:3], v[6:7], v[130:131], v[2:3]
	v_pk_fma_f32 v[0:1], v[4:5], v[126:127], v[0:1]
	v_pk_fma_f32 v[26:27], v[10:11], v[136:137], v[26:27]
	v_pk_fma_f32 v[30:31], v[8:9], v[138:139], v[30:31]
	v_pk_fma_f32 v[2:3], v[10:11], v[134:135], v[2:3]
	v_pk_fma_f32 v[18:19], v[14:15], v[18:19], v[26:27]
	v_pk_fma_f32 v[16:17], v[12:13], v[16:17], v[30:31]
	v_mul_f32_e32 v30, 0xbfb8aa3b, v18
	v_mul_f32_e32 v31, 0xbfb8aa3b, v19
	v_exp_f32_e32 v30, v30
	v_exp_f32_e32 v31, v31
	v_mul_f32_e32 v26, 0xbfb8aa3b, v16
	v_mul_f32_e32 v27, 0xbfb8aa3b, v17
	v_exp_f32_e32 v26, v26
	v_pk_add_f32 v[30:31], v[30:31], 1.0 op_sel_hi:[1,0]
	v_exp_f32_e32 v27, v27
	v_div_scale_f32 v85, s[8:9], v31, v31, 1.0
	v_rcp_f32_e32 v89, v85
	v_pk_add_f32 v[26:27], v[26:27], 1.0 op_sel_hi:[1,0]
	v_pk_fma_f32 v[2:3], v[14:15], v[136:137], v[2:3]
	v_pk_fma_f32 v[0:1], v[8:9], v[132:133], v[0:1]
	v_fma_f32 v91, -v85, v89, 1.0
	v_fmac_f32_e32 v89, v91, v89
	v_div_scale_f32 v91, vcc, 1.0, v31, 1.0
	v_mul_f32_e32 v93, v91, v89
	v_fma_f32 v102, -v85, v93, v91
	v_fmac_f32_e32 v93, v102, v89
	v_fma_f32 v85, -v85, v93, v91
	v_div_fmas_f32 v85, v85, v89, v93
	v_div_fixup_f32 v31, v85, v31, 1.0
	v_div_scale_f32 v85, s[8:9], v30, v30, 1.0
	v_rcp_f32_e32 v89, v85
	v_mul_f32_e32 v6, 0xbfb8aa3b, v2
	v_mul_f32_e32 v7, 0xbfb8aa3b, v3
	v_exp_f32_e32 v6, v6
	v_fma_f32 v91, -v85, v89, 1.0
	v_fmac_f32_e32 v89, v91, v89
	v_div_scale_f32 v91, vcc, 1.0, v30, 1.0
	v_mul_f32_e32 v93, v91, v89
	v_fma_f32 v102, -v85, v93, v91
	v_fmac_f32_e32 v93, v102, v89
	v_fma_f32 v85, -v85, v93, v91
	v_div_fmas_f32 v85, v85, v89, v93
	v_div_fixup_f32 v30, v85, v30, 1.0
	v_div_scale_f32 v85, s[8:9], v27, v27, 1.0
	v_rcp_f32_e32 v89, v85
	v_pk_mul_f32 v[104:105], v[18:19], v[30:31]
	v_exp_f32_e32 v7, v7
	v_pk_fma_f32 v[0:1], v[12:13], v[138:139], v[0:1]
	v_fma_f32 v91, -v85, v89, 1.0
	v_fmac_f32_e32 v89, v91, v89
	v_div_scale_f32 v91, vcc, 1.0, v27, 1.0
	v_mul_f32_e32 v93, v91, v89
	v_fma_f32 v102, -v85, v93, v91
	v_fmac_f32_e32 v93, v102, v89
	v_fma_f32 v85, -v85, v93, v91
	v_div_fmas_f32 v85, v85, v89, v93
	v_div_fixup_f32 v27, v85, v27, 1.0
	v_div_scale_f32 v85, s[8:9], v26, v26, 1.0
	v_rcp_f32_e32 v89, v85
	v_pk_add_f32 v[6:7], v[6:7], 1.0 op_sel_hi:[1,0]
	v_mul_f32_e32 v4, 0xbfb8aa3b, v0
	v_div_scale_f32 v8, s[8:9], v7, v7, 1.0
	v_fma_f32 v91, -v85, v89, 1.0
	v_fmac_f32_e32 v89, v91, v89
	v_div_scale_f32 v91, vcc, 1.0, v26, 1.0
	v_mul_f32_e32 v93, v91, v89
	v_fma_f32 v102, -v85, v93, v91
	v_fmac_f32_e32 v93, v102, v89
	v_fma_f32 v85, -v85, v93, v91
	v_div_fmas_f32 v85, v85, v89, v93
	v_div_fixup_f32 v26, v85, v26, 1.0
	v_pk_mul_f32 v[102:103], v[16:17], v[26:27]
	ds_read_b128 v[16:19], v233 offset:2064
	ds_read_b128 v[20:23], v233 offset:2576
	ds_read_b128 v[24:27], v233 offset:3088
	ds_read_b128 v[28:31], v233 offset:3600
	v_rcp_f32_e32 v9, v8
	v_mul_f32_e32 v5, 0xbfb8aa3b, v1
	v_exp_f32_e32 v4, v4
	v_exp_f32_e32 v5, v5
	v_fma_f32 v10, -v8, v9, 1.0
	v_fmac_f32_e32 v9, v10, v9
	v_pk_mul_f32 v[140:141], v[102:103], v[102:103]
	v_pk_add_f32 v[4:5], v[4:5], 1.0 op_sel_hi:[1,0]
	v_pk_mul_f32 v[122:123], v[104:105], v[104:105]
	s_waitcnt vmcnt(0) lgkmcnt(0)
; __device__ __forceinline__ float bflo(unsigned w) { return __uint_as_float(w << 16); }
; __device__ __forceinline__ float bfhi(unsigned w) { return __uint_as_float(w & 0xffff0000u); }
; __device__ __forceinline__ float sigmoidf_(float x) { return __frcp_rn(1.f + __expf(-x)); }
; __device__ __forceinline__ void prepB(const Params& p, int h, int n, char* shmc, int tid, int wv) {
;     ...
; #pragma unroll
;       for (int rr = 0; rr < 5; ++rr) {
;         const uint4 raw = rawv[rr];
;         const unsigned rw[4] = {raw.x, raw.y, raw.z, raw.w};
;         float xv[8];
; #pragma unroll
;         for (int i = 0; i < 4; ++i) { xv[2 * i] = bflo(rw[i]); xv[2 * i + 1] = bfhi(rw[i]); }
; #pragma unroll
;         for (int tt = 0; tt < 2; ++tt) {
;           const int j = rr - tt;
;           if (j >= 0 && j < 4) {
; #pragma unroll
;             for (int i = 0; i < 8; ++i) out[tt][i] += w[j][i] * xv[i];
;           }
;         }
;       }
; #pragma unroll
;       for (int tt = 0; tt < 2; ++tt) {
;         const int t = t0 + tt;
;         float ss = 0.f;
; #pragma unroll
;         for (int i = 0; i < 8; ++i) { const float o = out[tt][i]; out[tt][i] = o * sigmoidf_(o); ss += out[tt][i] * out[tt][i]; }
	v_pk_fma_f32 v[148:149], v[16:17], v[110:111], 0 op_sel_hi:[1,1,0]
	s_nop 0
	v_pk_fma_f32 v[148:149], v[20:21], v[114:115], v[148:149]
	v_pk_fma_f32 v[146:147], v[18:19], v[112:113], 0 op_sel_hi:[1,1,0]
	v_pk_fma_f32 v[148:149], v[24:25], v[120:121], v[148:149]
	v_pk_fma_f32 v[146:147], v[22:23], v[116:117], v[146:147]
	v_pk_fma_f32 v[142:143], v[28:29], v[142:143], v[148:149]
	v_pk_fma_f32 v[146:147], v[26:27], v[118:119], v[146:147]
	v_mul_f32_e32 v85, 0xbfb8aa3b, v142
	v_pk_fma_f32 v[144:145], v[30:31], v[144:145], v[146:147]
	v_exp_f32_e32 v146, v85
	v_mul_f32_e32 v85, 0xbfb8aa3b, v143
	v_exp_f32_e32 v147, v85
	v_mul_f32_e32 v85, 0xbfb8aa3b, v144
	v_exp_f32_e32 v148, v85
	v_mul_f32_e32 v85, 0xbfb8aa3b, v145
	v_exp_f32_e32 v149, v85
	v_pk_add_f32 v[146:147], v[146:147], 1.0 op_sel_hi:[1,0]
	v_pk_add_f32 v[148:149], v[148:149], 1.0 op_sel_hi:[1,0]
	s_nop 0
	v_div_scale_f32 v85, s[8:9], v149, v149, 1.0
	v_rcp_f32_e32 v89, v85
	s_nop 0
	v_fma_f32 v91, -v85, v89, 1.0
	v_fmac_f32_e32 v89, v91, v89
	v_div_scale_f32 v91, vcc, 1.0, v149, 1.0
	v_mul_f32_e32 v93, v91, v89
	v_fma_f32 v150, -v85, v93, v91
	v_fmac_f32_e32 v93, v150, v89
	v_fma_f32 v85, -v85, v93, v91
	v_div_fmas_f32 v85, v85, v89, v93
	v_div_fixup_f32 v149, v85, v149, 1.0
	v_div_scale_f32 v85, s[8:9], v148, v148, 1.0
	v_rcp_f32_e32 v89, v85
	s_nop 0
	v_fma_f32 v91, -v85, v89, 1.0
	v_fmac_f32_e32 v89, v91, v89
	v_div_scale_f32 v91, vcc, 1.0, v148, 1.0
	v_mul_f32_e32 v93, v91, v89
	v_fma_f32 v150, -v85, v93, v91
	v_fmac_f32_e32 v93, v150, v89
	v_fma_f32 v85, -v85, v93, v91
	v_div_fmas_f32 v85, v85, v89, v93
	v_div_fixup_f32 v148, v85, v148, 1.0
	v_div_scale_f32 v85, s[8:9], v147, v147, 1.0
	v_rcp_f32_e32 v89, v85
	v_pk_mul_f32 v[144:145], v[144:145], v[148:149]
	v_fma_f32 v91, -v85, v89, 1.0
	v_fmac_f32_e32 v89, v91, v89
	v_div_scale_f32 v91, vcc, 1.0, v147, 1.0
	v_mul_f32_e32 v93, v91, v89
	v_fma_f32 v150, -v85, v93, v91
	v_fmac_f32_e32 v93, v150, v89
	v_fma_f32 v85, -v85, v93, v91
	v_div_fmas_f32 v85, v85, v89, v93
	v_div_fixup_f32 v147, v85, v147, 1.0
	v_div_scale_f32 v85, s[8:9], v146, v146, 1.0
	v_rcp_f32_e32 v89, v85
	s_nop 0
	v_fma_f32 v91, -v85, v89, 1.0
	v_fmac_f32_e32 v89, v91, v89
	v_div_scale_f32 v91, vcc, 1.0, v146, 1.0
	v_mul_f32_e32 v93, v91, v89
	v_fma_f32 v150, -v85, v93, v91
	v_fmac_f32_e32 v93, v150, v89
	v_fma_f32 v85, -v85, v93, v91
	v_div_fmas_f32 v85, v85, v89, v93
	v_div_scale_f32 v10, vcc, 1.0, v7, 1.0
	v_mul_f32_e32 v11, v10, v9
	v_fma_f32 v12, -v8, v11, v10
	v_fmac_f32_e32 v11, v12, v9
	v_fma_f32 v8, -v8, v11, v10
	v_div_fmas_f32 v8, v8, v9, v11
	v_div_fixup_f32 v7, v8, v7, 1.0
	v_div_scale_f32 v8, s[8:9], v6, v6, 1.0
	v_rcp_f32_e32 v9, v8
	v_div_fixup_f32 v146, v85, v146, 1.0
	v_pk_mul_f32 v[142:143], v[142:143], v[146:147]
	v_pk_mul_f32 v[146:147], v[144:145], v[144:145]
	v_fma_f32 v10, -v8, v9, 1.0
	v_fmac_f32_e32 v9, v10, v9
	v_div_scale_f32 v10, vcc, 1.0, v6, 1.0
	v_mul_f32_e32 v11, v10, v9
	v_fma_f32 v12, -v8, v11, v10
	v_fmac_f32_e32 v11, v12, v9
	v_fma_f32 v8, -v8, v11, v10
	v_div_fmas_f32 v8, v8, v9, v11
	v_div_fixup_f32 v6, v8, v6, 1.0
	v_div_scale_f32 v8, s[8:9], v5, v5, 1.0
	v_rcp_f32_e32 v9, v8
	v_pk_mul_f32 v[2:3], v[2:3], v[6:7]
	v_pk_mul_f32 v[148:149], v[142:143], v[142:143]
	v_fma_f32 v10, -v8, v9, 1.0
	v_fmac_f32_e32 v9, v10, v9
	v_div_scale_f32 v10, vcc, 1.0, v5, 1.0
	v_mul_f32_e32 v11, v10, v9
	v_fma_f32 v12, -v8, v11, v10
	v_fmac_f32_e32 v11, v12, v9
	v_fma_f32 v8, -v8, v11, v10
	v_div_fmas_f32 v8, v8, v9, v11
	v_div_fixup_f32 v5, v8, v5, 1.0
	v_div_scale_f32 v8, s[8:9], v4, v4, 1.0
	v_rcp_f32_e32 v9, v8
	s_nop 0
	v_fma_f32 v10, -v8, v9, 1.0
	v_fmac_f32_e32 v9, v10, v9
	v_div_scale_f32 v10, vcc, 1.0, v4, 1.0
	v_mul_f32_e32 v11, v10, v9
	v_fma_f32 v12, -v8, v11, v10
	v_fmac_f32_e32 v11, v12, v9
	v_fma_f32 v8, -v8, v11, v10
	v_div_fmas_f32 v8, v8, v9, v11
	v_div_fixup_f32 v4, v8, v4, 1.0
	v_pk_mul_f32 v[0:1], v[0:1], v[4:5]
	v_mov_b32_e32 v8, v140
	v_pk_mul_f32 v[6:7], v[0:1], v[0:1]
	v_pk_fma_f32 v[10:11], v[16:17], v[106:107], 0 op_sel_hi:[1,1,0]
	v_mov_b32_e32 v9, v6
	v_mov_b32_e32 v6, v141
	v_pk_add_f32 v[6:7], v[8:9], v[6:7]
	v_pk_fma_f32 v[8:9], v[18:19], v[108:109], 0 op_sel_hi:[1,1,0]
	v_pk_fma_f32 v[10:11], v[20:21], v[110:111], v[10:11]
	v_pk_fma_f32 v[8:9], v[22:23], v[112:113], v[8:9]
	v_pk_fma_f32 v[10:11], v[24:25], v[114:115], v[10:11]
	v_pk_fma_f32 v[8:9], v[26:27], v[116:117], v[8:9]
	v_pk_fma_f32 v[10:11], v[28:29], v[120:121], v[10:11]
	v_pk_fma_f32 v[8:9], v[30:31], v[118:119], v[8:9]
	v_mul_f32_e32 v12, 0xbfb8aa3b, v10
	v_mul_f32_e32 v14, 0xbfb8aa3b, v8
	v_mul_f32_e32 v15, 0xbfb8aa3b, v9
	v_exp_f32_e32 v14, v14
; __device__ __forceinline__ unsigned pack2(float a, float b) { const f32v2_ v = {a, b}; const bf16v2_ r = __builtin_convertvector(v, bf16v2_); return __builtin_bit_cast(unsigned, r); }
; __device__ __forceinline__ float shfl_idx(float v, int srclane) { return __int_as_float(__builtin_amdgcn_ds_bpermute(srclane << 2, __float_as_int(v))); }
; __device__ __forceinline__ int perm32(int c) { return ((c >> 2) & 3) * 8 + ((c >> 4) & 1) * 4 + (c & 3); }
; __device__ __forceinline__ float sigmoidf_(float x) { return __frcp_rn(1.f + __expf(-x)); }
; __device__ __forceinline__ void prepB(const Params& p, int h, int n, char* shmc, int tid, int wv) {
;     ...
;       for (int tt = 0; tt < 2; ++tt) {
;         const int t = t0 + tt;
;         float ss = 0.f;
; #pragma unroll
;         for (int i = 0; i < 8; ++i) { const float o = out[tt][i]; out[tt][i] = o * sigmoidf_(o); ss += out[tt][i] * out[tt][i]; }
;         if (sig < 2) {
; #pragma unroll
;           for (int o = 1; o < 16; o <<= 1) ss += shfl_idx(ss, (tid & 63) ^ o);
;           const float rs = rsqrtf(ss + EPS_);
;           if (sig == 0) {
;             const float eg = __expf(gcS[t]);
;             float qn[8];
; #pragma unroll
;             for (int i = 0; i < 8; ++i) { qn[i] = out[tt][i] * rs * 0.08838834764831845f; qB[t * 136 + c0 + i] = f2bf(qn[i]); }
;             u16* qd = QPB + (long)tix * 8192;
; #pragma unroll
;             for (int g = 0; g < 2; ++g) {
;               uint2 o; o.x = pack2(qn[4 * g] * eg, qn[4 * g + 1] * eg); o.y = pack2(qn[4 * g + 2] * eg, qn[4 * g + 3] * eg);
;               const int p0 = (c0 & ~31) + perm32((c0 & 31) + 4 * g);
;               *(uint2*)(qd + ((((t >> 4) * 4 + (p0 >> 5)) * 64 + ((p0 >> 3) & 3) * 16 + (t & 15)) * 8) + (p0 & 7)) = o;
;             }
;           } else {
; #pragma unroll
;             for (int i = 0; i < 8; ++i) { const float kn = out[tt][i] * rs; kF[t * 128 + c0 + i] = kn; kB[t * 136 + c0 + i] = f2bf(kn); }
;           }
	v_exp_f32_e32 v15, v15
	v_mul_f32_e32 v13, 0xbfb8aa3b, v11
	v_exp_f32_e32 v12, v12
	v_exp_f32_e32 v13, v13
	v_pk_add_f32 v[14:15], v[14:15], 1.0 op_sel_hi:[1,0]
	v_pk_mul_f32 v[4:5], v[2:3], v[2:3]
	v_div_scale_f32 v16, s[8:9], v15, v15, 1.0
	v_rcp_f32_e32 v17, v16
	v_pk_add_f32 v[12:13], v[12:13], 1.0 op_sel_hi:[1,0]
	v_or_b32_e32 v22, 0x800, v87
	v_lshlrev_b32_e32 v212, 1, v22
	v_fma_f32 v18, -v16, v17, 1.0
	v_fmac_f32_e32 v17, v18, v17
	v_div_scale_f32 v18, vcc, 1.0, v15, 1.0
	v_mul_f32_e32 v19, v18, v17
	v_fma_f32 v20, -v16, v19, v18
	v_fmac_f32_e32 v19, v20, v17
	v_fma_f32 v16, -v16, v19, v18
	v_div_fmas_f32 v16, v16, v17, v19
	v_div_fixup_f32 v15, v16, v15, 1.0
	v_div_scale_f32 v16, s[8:9], v14, v14, 1.0
	v_rcp_f32_e32 v17, v16
	s_nop 0
	v_fma_f32 v18, -v16, v17, 1.0
	v_fmac_f32_e32 v17, v18, v17
	v_div_scale_f32 v18, vcc, 1.0, v14, 1.0
	v_mul_f32_e32 v19, v18, v17
	v_fma_f32 v20, -v16, v19, v18
	v_fmac_f32_e32 v19, v20, v17
	v_fma_f32 v16, -v16, v19, v18
	v_div_fmas_f32 v16, v16, v17, v19
	v_div_fixup_f32 v14, v16, v14, 1.0
	v_div_scale_f32 v16, s[8:9], v13, v13, 1.0
	v_rcp_f32_e32 v17, v16
	v_pk_mul_f32 v[8:9], v[8:9], v[14:15]
	v_fma_f32 v18, -v16, v17, 1.0
	v_fmac_f32_e32 v17, v18, v17
	v_div_scale_f32 v18, vcc, 1.0, v13, 1.0
	v_mul_f32_e32 v19, v18, v17
	v_fma_f32 v20, -v16, v19, v18
	v_fmac_f32_e32 v19, v20, v17
	v_fma_f32 v16, -v16, v19, v18
	v_div_fmas_f32 v16, v16, v17, v19
	v_div_fixup_f32 v13, v16, v13, 1.0
	v_div_scale_f32 v16, s[8:9], v12, v12, 1.0
	v_rcp_f32_e32 v17, v16
	s_mov_b32 s8, 0x358637bd
	v_fma_f32 v18, -v16, v17, 1.0
	v_fmac_f32_e32 v17, v18, v17
	v_div_scale_f32 v18, vcc, 1.0, v12, 1.0
	v_mul_f32_e32 v19, v18, v17
	v_fma_f32 v20, -v16, v19, v18
	v_fmac_f32_e32 v19, v20, v17
	v_fma_f32 v16, -v16, v19, v18
	v_div_fmas_f32 v16, v16, v17, v19
	v_div_fixup_f32 v12, v16, v12, 1.0
	v_pk_mul_f32 v[10:11], v[10:11], v[12:13]
	v_mov_b32_e32 v16, v122
	v_mov_b32_e32 v17, v4
	v_pk_mul_f32 v[14:15], v[10:11], v[10:11]
	v_pk_add_f32 v[6:7], v[6:7], v[16:17]
	v_mov_b32_e32 v4, v123
	v_pk_add_f32 v[4:5], v[6:7], v[4:5]
	v_mov_b32_e32 v6, v148
	v_mov_b32_e32 v7, v14
	v_pk_mul_f32 v[12:13], v[8:9], v[8:9]
	v_pk_add_f32 v[4:5], v[4:5], v[6:7]
	v_mov_b32_e32 v14, v149
	v_pk_add_f32 v[4:5], v[4:5], v[14:15]
	v_mov_b32_e32 v6, v146
	v_mov_b32_e32 v7, v12
	v_pk_add_f32 v[4:5], v[4:5], v[6:7]
	v_mov_b32_e32 v12, v147
	v_pk_add_f32 v[4:5], v[4:5], v[12:13]
	ds_bpermute_b32 v7, v157, v5
	ds_bpermute_b32 v6, v157, v4
	v_lshl_add_u64 v[20:21], v[36:37], 0, v[212:213]
	s_waitcnt lgkmcnt(0)
	v_pk_add_f32 v[4:5], v[4:5], v[6:7]
	ds_bpermute_b32 v7, v158, v5
	ds_bpermute_b32 v6, v158, v4
	s_waitcnt lgkmcnt(0)
	v_pk_add_f32 v[4:5], v[4:5], v[6:7]
	ds_bpermute_b32 v7, v159, v5
	ds_bpermute_b32 v6, v159, v4
	s_waitcnt lgkmcnt(0)
	v_pk_add_f32 v[4:5], v[4:5], v[6:7]
	ds_bpermute_b32 v7, v160, v5
	ds_bpermute_b32 v6, v160, v4
	s_waitcnt lgkmcnt(0)
	v_pk_add_f32 v[4:5], v[4:5], v[6:7]
	s_nop 0
	v_pk_add_f32 v[12:13], v[4:5], s[8:9] op_sel_hi:[1,0]
	s_nop 0
	v_mul_f32_e32 v4, 0x4b800000, v13
	v_cmp_gt_f32_e64 s[86:87], s70, v13
	v_cmp_gt_f32_e32 vcc, s70, v12
	s_nop 0
	v_cndmask_b32_e64 v4, v13, v4, s[86:87]
	v_rsq_f32_e32 v4, v4
	v_add_u32_e32 v13, v73, v162
	v_mul_f32_e32 v5, 0x45800000, v4
	v_cndmask_b32_e64 v6, v4, v5, s[86:87]
	v_pk_mul_f32 v[0:1], v[0:1], v[6:7] op_sel_hi:[1,0]
	v_pk_mul_f32 v[2:3], v[2:3], v[6:7] op_sel_hi:[1,0]
	v_pk_mul_f32 v[4:5], v[10:11], v[6:7] op_sel_hi:[1,0]
	v_pk_mul_f32 v[6:7], v[8:9], v[6:7] op_sel_hi:[1,0]
	ds_write_b128 v240, v[0:3]
	ds_write_b128 v240, v[4:7] offset:16
	v_cvt_pk_bf16_f32 v7, v6, v7
	v_cvt_pk_bf16_f32 v6, v4, v5
	v_cvt_pk_bf16_f32 v4, v0, v1
	v_mul_f32_e32 v0, 0x4b800000, v12
	v_cndmask_b32_e32 v0, v12, v0, vcc
	v_rsq_f32_e32 v0, v0
	v_cvt_pk_bf16_f32 v5, v2, v3
	ds_write_b128 v13, v[4:7]
	v_add_u32_e32 v8, v73, v164
	v_mul_f32_e32 v1, 0x45800000, v0
	v_cndmask_b32_e32 v6, v0, v1, vcc
	v_pk_mul_f32 v[0:1], v[102:103], v[6:7] op_sel_hi:[1,0]
	v_pk_mul_f32 v[2:3], v[104:105], v[6:7] op_sel_hi:[1,0]
	v_pk_mul_f32 v[4:5], v[142:143], v[6:7] op_sel_hi:[1,0]
	v_pk_mul_f32 v[6:7], v[144:145], v[6:7] op_sel_hi:[1,0]
	ds_write_b128 v241, v[4:7] offset:16
	v_cvt_pk_bf16_f32 v7, v6, v7
	v_cvt_pk_bf16_f32 v6, v4, v5
	v_cvt_pk_bf16_f32 v5, v2, v3
	v_cvt_pk_bf16_f32 v4, v0, v1
	ds_write_b128 v241, v[0:3]
	ds_write_b128 v8, v[4:7]
	v_mov_b32_e32 v3, 0
	v_mov_b32_e32 v7, 0
	v_mov_b32_e32 v6, 0
	v_mov_b32_e32 v5, 0
	v_mov_b32_e32 v4, 0
	s_and_saveexec_b64 s[86:87], s[76:77]
	s_cbranch_execz .LBB0_458
	v_mad_u64_u32 v[0:1], s[8:9], v34, s42, v[20:21]
	v_mad_i32_i24 v1, v35, s42, v1
	global_load_dwordx4 v[4:7], v[0:1], off

; __device__ __forceinline__ float bflo(unsigned w) { return __uint_as_float(w << 16); }
; __device__ __forceinline__ float bfhi(unsigned w) { return __uint_as_float(w & 0xffff0000u); }
; __device__ __forceinline__ uint4 ldg16(const void* p) { const u32x4 v = *(const __attribute__((address_space(1))) u32x4*)(p); return make_uint4(v.x, v.y, v.z, v.w); }
; __device__ __forceinline__ void prepB(const Params& p, int h, int n, char* shmc, int tid, int wv) {
;     ...
;       const int colg = sig * 1024 + h * 128 + c0;
;       uint4 rawv[5];
; #pragma unroll
;       for (int rr = 0; rr < 5; ++rr) {
;         const long tok = rowbase + t0 - 3 + rr;
;         rawv[rr] = make_uint4(0u, 0u, 0u, 0u);
;         if (tok >= 0) rawv[rr] = ldg16(GQKV + tok * 3072 + colg);
;       }
;       float w[4][8];
; #pragma unroll
;       for (int j = 0; j < 4; ++j) {
;         const float4 wa = *(const float4*)(p.a_conv_w + j * 3072 + colg), wb = *(const float4*)(p.a_conv_w + j * 3072 + colg + 4);
;         w[j][0] = wa.x; w[j][1] = wa.y; w[j][2] = wa.z; w[j][3] = wa.w; w[j][4] = wb.x; w[j][5] = wb.y; w[j][6] = wb.z; w[j][7] = wb.w;
;       }
;       float out[2][8];
; #pragma unroll
;       for (int tt = 0; tt < 2; ++tt)
; #pragma unroll
;         for (int i = 0; i < 8; ++i) out[tt][i] = 0.f;
; #pragma unroll
;       for (int rr = 0; rr < 5; ++rr) {
;         const uint4 raw = rawv[rr];
;         const unsigned rw[4] = {raw.x, raw.y, raw.z, raw.w};
;         float xv[8];
; #pragma unroll
;         for (int i = 0; i < 4; ++i) { xv[2 * i] = bflo(rw[i]); xv[2 * i + 1] = bfhi(rw[i]); }
; #pragma unroll
;         for (int tt = 0; tt < 2; ++tt) {
;           const int j = rr - tt;
;           if (j >= 0 && j < 4) {
; #pragma unroll
;             for (int i = 0; i < 8; ++i) out[tt][i] += w[j][i] * xv[i];
;           }
;         }
;       }
.LBB0_466:
	s_or_b64 exec, exec, s[76:77]
	v_lshlrev_b32_e32 v212, 2, v22
	s_waitcnt vmcnt(0)
	v_and_b32_e32 v97, 0xffff0000, v7
	v_lshlrev_b32_e32 v96, 16, v7
	v_and_b32_e32 v105, 0xffff0000, v6
	v_lshlrev_b32_e32 v104, 16, v6
	v_and_b32_e32 v113, 0xffff0000, v5
	v_lshlrev_b32_e32 v112, 16, v5
	v_and_b32_e32 v121, 0xffff0000, v4
	v_lshlrev_b32_e32 v120, 16, v4
	ds_read_b128 v[4:7], v233 offset:4096
	v_lshlrev_b32_e32 v126, 16, v8
	v_and_b32_e32 v127, 0xffff0000, v8
	v_lshlrev_b32_e32 v118, 16, v9
	v_and_b32_e32 v119, 0xffff0000, v9
	v_lshlrev_b32_e32 v110, 16, v10
	v_and_b32_e32 v111, 0xffff0000, v10
	v_lshlrev_b32_e32 v102, 16, v11
	v_and_b32_e32 v103, 0xffff0000, v11
	ds_read_b128 v[8:11], v233 offset:4608
	v_lshlrev_b32_e32 v124, 16, v12
	v_and_b32_e32 v125, 0xffff0000, v12
	v_lshlrev_b32_e32 v116, 16, v13
	v_and_b32_e32 v117, 0xffff0000, v13
	v_lshlrev_b32_e32 v108, 16, v14
	v_and_b32_e32 v109, 0xffff0000, v14
	v_lshlrev_b32_e32 v100, 16, v15
	v_and_b32_e32 v101, 0xffff0000, v15
	ds_read_b128 v[12:15], v233 offset:5120
	v_lshlrev_b32_e32 v122, 16, v0
	v_and_b32_e32 v123, 0xffff0000, v0
	v_lshlrev_b32_e32 v114, 16, v1
	v_and_b32_e32 v115, 0xffff0000, v1
	v_lshlrev_b32_e32 v106, 16, v2
	v_and_b32_e32 v107, 0xffff0000, v2
	v_lshlrev_b32_e32 v98, 16, v3
	v_and_b32_e32 v99, 0xffff0000, v3
	v_lshlrev_b32_e32 v0, 16, v16
	v_and_b32_e32 v1, 0xffff0000, v16
	v_lshlrev_b32_e32 v2, 16, v17
	v_and_b32_e32 v3, 0xffff0000, v17
	v_lshlrev_b32_e32 v36, 16, v18
	v_and_b32_e32 v37, 0xffff0000, v18
	v_lshlrev_b32_e32 v38, 16, v19
	v_and_b32_e32 v39, 0xffff0000, v19
	ds_read_b128 v[16:19], v233 offset:5632
	s_waitcnt vmcnt(0) lgkmcnt(0)
	v_pk_fma_f32 v[22:23], v[4:5], v[122:123], 0 op_sel_hi:[1,1,0]
	v_pk_fma_f32 v[4:5], v[4:5], v[120:121], 0 op_sel_hi:[1,1,0]
	v_pk_fma_f32 v[22:23], v[8:9], v[124:125], v[22:23]
	v_pk_fma_f32 v[4:5], v[8:9], v[122:123], v[4:5]
	v_pk_fma_f32 v[22:23], v[12:13], v[126:127], v[22:23]
	v_pk_fma_f32 v[4:5], v[12:13], v[124:125], v[4:5]
	v_pk_fma_f32 v[0:1], v[16:17], v[0:1], v[22:23]
	s_nop 0
	v_mul_f32_e32 v22, 0xbfb8aa3b, v1
	v_exp_f32_e32 v23, v22
	v_mul_f32_e32 v22, 0xbfb8aa3b, v0
	v_exp_f32_e32 v22, v22
	v_pk_fma_f32 v[4:5], v[16:17], v[126:127], v[4:5]
	v_pk_add_f32 v[22:23], v[22:23], 1.0 op_sel_hi:[1,0]
	s_nop 0
	v_div_scale_f32 v26, s[8:9], v23, v23, 1.0
	v_rcp_f32_e32 v27, v26
	v_mul_f32_e32 v8, 0xbfb8aa3b, v5
	v_exp_f32_e32 v9, v8
	v_mul_f32_e32 v8, 0xbfb8aa3b, v4
	v_fma_f32 v30, -v26, v27, 1.0
	v_fmac_f32_e32 v27, v30, v27
	v_div_scale_f32 v30, vcc, 1.0, v23, 1.0
	v_mul_f32_e32 v31, v30, v27
	v_fma_f32 v34, -v26, v31, v30
	v_fmac_f32_e32 v31, v34, v27
	v_fma_f32 v26, -v26, v31, v30
	v_div_fmas_f32 v26, v26, v27, v31
	v_div_fixup_f32 v23, v26, v23, 1.0
	v_div_scale_f32 v26, s[8:9], v22, v22, 1.0
	v_rcp_f32_e32 v27, v26
	v_exp_f32_e32 v8, v8
	v_fma_f32 v30, -v26, v27, 1.0
	v_fmac_f32_e32 v27, v30, v27
	v_div_scale_f32 v30, vcc, 1.0, v22, 1.0
	v_mul_f32_e32 v31, v30, v27
	v_fma_f32 v34, -v26, v31, v30
	v_fmac_f32_e32 v31, v34, v27
	v_fma_f32 v26, -v26, v31, v30
	v_div_fmas_f32 v26, v26, v27, v31
	v_div_fixup_f32 v22, v26, v22, 1.0
	v_pk_mul_f32 v[0:1], v[0:1], v[22:23]
	v_pk_fma_f32 v[22:23], v[6:7], v[114:115], 0 op_sel_hi:[1,1,0]
	v_pk_add_f32 v[8:9], v[8:9], 1.0 op_sel_hi:[1,0]
	v_pk_fma_f32 v[22:23], v[10:11], v[116:117], v[22:23]
	v_div_scale_f32 v12, s[8:9], v9, v9, 1.0
	v_pk_fma_f32 v[22:23], v[14:15], v[118:119], v[22:23]
	v_rcp_f32_e32 v13, v12
	v_pk_fma_f32 v[2:3], v[18:19], v[2:3], v[22:23]
	v_pk_fma_f32 v[6:7], v[6:7], v[112:113], 0 op_sel_hi:[1,1,0]
	v_mul_f32_e32 v22, 0xbfb8aa3b, v3
	v_exp_f32_e32 v23, v22
	v_mul_f32_e32 v22, 0xbfb8aa3b, v2
	v_exp_f32_e32 v22, v22
	v_fma_f32 v16, -v12, v13, 1.0
	v_fmac_f32_e32 v13, v16, v13
	v_pk_fma_f32 v[6:7], v[10:11], v[114:115], v[6:7]
	v_pk_add_f32 v[22:23], v[22:23], 1.0 op_sel_hi:[1,0]
	v_pk_fma_f32 v[6:7], v[14:15], v[116:117], v[6:7]
	v_div_scale_f32 v26, s[8:9], v23, v23, 1.0
	v_rcp_f32_e32 v27, v26
	v_pk_fma_f32 v[6:7], v[18:19], v[118:119], v[6:7]
	v_fma_f32 v30, -v26, v27, 1.0
	v_fmac_f32_e32 v27, v30, v27
	v_div_scale_f32 v30, vcc, 1.0, v23, 1.0
	v_mul_f32_e32 v31, v30, v27
	v_fma_f32 v34, -v26, v31, v30
	v_fmac_f32_e32 v31, v34, v27
	v_fma_f32 v26, -v26, v31, v30
	v_div_fmas_f32 v26, v26, v27, v31
	v_div_fixup_f32 v23, v26, v23, 1.0
	v_div_scale_f32 v26, s[8:9], v22, v22, 1.0
	v_rcp_f32_e32 v27, v26
	s_nop 0
	v_fma_f32 v30, -v26, v27, 1.0
	v_fmac_f32_e32 v27, v30, v27
	v_div_scale_f32 v30, vcc, 1.0, v22, 1.0
	v_mul_f32_e32 v31, v30, v27
	v_fma_f32 v34, -v26, v31, v30
	v_fmac_f32_e32 v31, v34, v27
	v_fma_f32 v26, -v26, v31, v30
	v_div_fmas_f32 v26, v26, v27, v31
	v_div_fixup_f32 v22, v26, v22, 1.0
	v_pk_mul_f32 v[2:3], v[2:3], v[22:23]
	ds_read_b128 v[20:23], v233 offset:4112
	ds_read_b128 v[24:27], v233 offset:4624
	ds_read_b128 v[28:31], v233 offset:5136
	ds_read_b128 v[32:35], v233 offset:5648
	s_waitcnt vmcnt(0) lgkmcnt(0)
; __device__ __forceinline__ unsigned pack2(float a, float b) { const f32v2_ v = {a, b}; const bf16v2_ r = __builtin_convertvector(v, bf16v2_); return __builtin_bit_cast(unsigned, r); }
; __device__ __forceinline__ float shfl_idx(float v, int srclane) { return __int_as_float(__builtin_amdgcn_ds_bpermute(srclane << 2, __float_as_int(v))); }
; __device__ __forceinline__ int perm32(int c) { return ((c >> 2) & 3) * 8 + ((c >> 4) & 1) * 4 + (c & 3); }
; __device__ __forceinline__ float sigmoidf_(float x) { return __frcp_rn(1.f + __expf(-x)); }
; __device__ __forceinline__ void prepB(const Params& p, int h, int n, char* shmc, int tid, int wv) {
;     ...
; #pragma unroll
;       for (int tt = 0; tt < 2; ++tt) {
;         const int t = t0 + tt;
;         float ss = 0.f;
; #pragma unroll
;         for (int i = 0; i < 8; ++i) { const float o = out[tt][i]; out[tt][i] = o * sigmoidf_(o); ss += out[tt][i] * out[tt][i]; }
;         if (sig < 2) {
; #pragma unroll
;           for (int o = 1; o < 16; o <<= 1) ss += shfl_idx(ss, (tid & 63) ^ o);
;           const float rs = rsqrtf(ss + EPS_);
;           if (sig == 0) {
;             const float eg = __expf(gcS[t]);
;             float qn[8];
; #pragma unroll
;             for (int i = 0; i < 8; ++i) { qn[i] = out[tt][i] * rs * 0.08838834764831845f; qB[t * 136 + c0 + i] = f2bf(qn[i]); }
;             u16* qd = QPB + (long)tix * 8192;
; #pragma unroll
;             for (int g = 0; g < 2; ++g) {
;               uint2 o; o.x = pack2(qn[4 * g] * eg, qn[4 * g + 1] * eg); o.y = pack2(qn[4 * g + 2] * eg, qn[4 * g + 3] * eg);
;               const int p0 = (c0 & ~31) + perm32((c0 & 31) + 4 * g);
;               *(uint2*)(qd + ((((t >> 4) * 4 + (p0 >> 5)) * 64 + ((p0 >> 3) & 3) * 16 + (t & 15)) * 8) + (p0 & 7)) = o;
;             }
;           } else {
; #pragma unroll
;             for (int i = 0; i < 8; ++i) { const float kn = out[tt][i] * rs; kF[t * 128 + c0 + i] = kn; kB[t * 136 + c0 + i] = f2bf(kn); }
;           }
;         } else {
; #pragma unroll
;           for (int i = 0; i < 8; ++i) vF[t * 128 + c0 + i] = out[tt][i];
;         }
;       }
;     }
;   }
;   __syncthreads();
	v_pk_fma_f32 v[128:129], v[20:21], v[106:107], 0 op_sel_hi:[1,1,0]
	s_nop 0
	v_pk_fma_f32 v[128:129], v[24:25], v[108:109], v[128:129]
	s_nop 0
	v_pk_fma_f32 v[128:129], v[28:29], v[110:111], v[128:129]
	s_nop 0
	v_pk_fma_f32 v[36:37], v[32:33], v[36:37], v[128:129]
	s_nop 0
	v_mul_f32_e32 v87, 0xbfb8aa3b, v37
	v_exp_f32_e32 v129, v87
	v_mul_f32_e32 v87, 0xbfb8aa3b, v36
	v_exp_f32_e32 v128, v87
	s_nop 0
	v_pk_add_f32 v[128:129], v[128:129], 1.0 op_sel_hi:[1,0]
	s_nop 0
	v_div_scale_f32 v87, s[8:9], v129, v129, 1.0
	v_rcp_f32_e32 v89, v87
	s_nop 0
	v_fma_f32 v91, -v87, v89, 1.0
	v_fmac_f32_e32 v89, v91, v89
	v_div_scale_f32 v91, vcc, 1.0, v129, 1.0
	v_mul_f32_e32 v93, v91, v89
	v_fma_f32 v130, -v87, v93, v91
	v_fmac_f32_e32 v93, v130, v89
	v_fma_f32 v87, -v87, v93, v91
	v_div_fmas_f32 v87, v87, v89, v93
	v_div_fixup_f32 v129, v87, v129, 1.0
	v_div_scale_f32 v87, s[8:9], v128, v128, 1.0
	v_rcp_f32_e32 v89, v87
	s_nop 0
	v_fma_f32 v91, -v87, v89, 1.0
	v_fmac_f32_e32 v89, v91, v89
	v_div_scale_f32 v91, vcc, 1.0, v128, 1.0
	v_mul_f32_e32 v93, v91, v89
	v_fma_f32 v130, -v87, v93, v91
	v_fmac_f32_e32 v93, v130, v89
	v_fma_f32 v87, -v87, v93, v91
	v_div_fmas_f32 v87, v87, v89, v93
	v_div_fixup_f32 v128, v87, v128, 1.0
	v_pk_mul_f32 v[36:37], v[36:37], v[128:129]
	v_pk_fma_f32 v[128:129], v[22:23], v[98:99], 0 op_sel_hi:[1,1,0]
	s_nop 0
	v_pk_fma_f32 v[128:129], v[26:27], v[100:101], v[128:129]
	s_nop 0
	v_pk_fma_f32 v[128:129], v[30:31], v[102:103], v[128:129]
	s_nop 0
	v_pk_fma_f32 v[38:39], v[34:35], v[38:39], v[128:129]
	s_nop 0
	v_mul_f32_e32 v87, 0xbfb8aa3b, v39
	v_exp_f32_e32 v129, v87
	v_mul_f32_e32 v87, 0xbfb8aa3b, v38
	v_exp_f32_e32 v128, v87
	s_nop 0
	v_pk_add_f32 v[128:129], v[128:129], 1.0 op_sel_hi:[1,0]
	s_nop 0
	v_div_scale_f32 v87, s[8:9], v129, v129, 1.0
	v_rcp_f32_e32 v89, v87
	s_nop 0
	v_fma_f32 v91, -v87, v89, 1.0
	v_fmac_f32_e32 v89, v91, v89
	v_div_scale_f32 v91, vcc, 1.0, v129, 1.0
	v_mul_f32_e32 v93, v91, v89
	v_fma_f32 v130, -v87, v93, v91
	v_fmac_f32_e32 v93, v130, v89
	v_fma_f32 v87, -v87, v93, v91
	v_div_fmas_f32 v87, v87, v89, v93
	v_div_fixup_f32 v129, v87, v129, 1.0
	v_div_scale_f32 v87, s[8:9], v128, v128, 1.0
	v_rcp_f32_e32 v89, v87
	s_nop 0
	v_fma_f32 v91, -v87, v89, 1.0
	v_fmac_f32_e32 v89, v91, v89
	v_div_scale_f32 v91, vcc, 1.0, v128, 1.0
	v_mul_f32_e32 v93, v91, v89
	v_fma_f32 v130, -v87, v93, v91
	v_fmac_f32_e32 v93, v130, v89
	v_fma_f32 v87, -v87, v93, v91
	v_div_fmas_f32 v87, v87, v89, v93
	v_div_scale_f32 v16, vcc, 1.0, v9, 1.0
	v_mul_f32_e32 v17, v16, v13
	v_div_fixup_f32 v128, v87, v128, 1.0
	v_fma_f32 v87, -v12, v17, v16
	v_fmac_f32_e32 v17, v87, v13
	v_fma_f32 v12, -v12, v17, v16
	v_div_fmas_f32 v12, v12, v13, v17
	v_div_fixup_f32 v9, v12, v9, 1.0
	v_div_scale_f32 v12, s[8:9], v8, v8, 1.0
	v_rcp_f32_e32 v13, v12
	v_pk_mul_f32 v[38:39], v[38:39], v[128:129]
	v_fma_f32 v16, -v12, v13, 1.0
	v_fmac_f32_e32 v13, v16, v13
	v_div_scale_f32 v16, vcc, 1.0, v8, 1.0
	v_mul_f32_e32 v17, v16, v13
	v_fma_f32 v87, -v12, v17, v16
	v_fmac_f32_e32 v17, v87, v13
	v_fma_f32 v12, -v12, v17, v16
	v_div_fmas_f32 v12, v12, v13, v17
	v_div_fixup_f32 v8, v12, v8, 1.0
	v_pk_mul_f32 v[4:5], v[4:5], v[8:9]
	v_mul_f32_e32 v8, 0xbfb8aa3b, v7
	v_exp_f32_e32 v9, v8
	v_mul_f32_e32 v8, 0xbfb8aa3b, v6
	v_exp_f32_e32 v8, v8
	s_nop 0
	v_pk_add_f32 v[8:9], v[8:9], 1.0 op_sel_hi:[1,0]
	s_nop 0
	v_div_scale_f32 v10, s[8:9], v9, v9, 1.0
	v_rcp_f32_e32 v11, v10
	s_nop 0
	v_fma_f32 v12, -v10, v11, 1.0
	v_fmac_f32_e32 v11, v12, v11
	v_div_scale_f32 v12, vcc, 1.0, v9, 1.0
	v_mul_f32_e32 v13, v12, v11
	v_fma_f32 v14, -v10, v13, v12
	v_fmac_f32_e32 v13, v14, v11
	v_fma_f32 v10, -v10, v13, v12
	v_div_fmas_f32 v10, v10, v11, v13
	v_div_fixup_f32 v9, v10, v9, 1.0
	v_div_scale_f32 v10, s[8:9], v8, v8, 1.0
	v_rcp_f32_e32 v11, v10
	s_nop 0
	v_fma_f32 v12, -v10, v11, 1.0
	v_fmac_f32_e32 v11, v12, v11
	v_div_scale_f32 v12, vcc, 1.0, v8, 1.0
	v_mul_f32_e32 v13, v12, v11
	v_fma_f32 v14, -v10, v13, v12
	v_fmac_f32_e32 v13, v14, v11
	v_fma_f32 v10, -v10, v13, v12
	v_div_fmas_f32 v10, v10, v11, v13
	v_div_fixup_f32 v8, v10, v8, 1.0
	v_pk_mul_f32 v[6:7], v[6:7], v[8:9]
	ds_write_b128 v240, v[4:7] offset:32768
	v_pk_fma_f32 v[4:5], v[20:21], v[104:105], 0 op_sel_hi:[1,1,0]
	s_nop 0
	v_pk_fma_f32 v[4:5], v[24:25], v[106:107], v[4:5]
	s_nop 0
	v_pk_fma_f32 v[4:5], v[28:29], v[108:109], v[4:5]
	v_add_u32_e32 v28, v165, v166
	v_pk_fma_f32 v[4:5], v[32:33], v[110:111], v[4:5]
	v_add_u32_e32 v29, v165, v169
	v_mul_f32_e32 v6, 0xbfb8aa3b, v5
	v_exp_f32_e32 v7, v6
	v_mul_f32_e32 v6, 0xbfb8aa3b, v4
	v_exp_f32_e32 v6, v6
	s_nop 0
	v_pk_add_f32 v[6:7], v[6:7], 1.0 op_sel_hi:[1,0]
	s_nop 0
	v_div_scale_f32 v8, s[8:9], v7, v7, 1.0
	v_rcp_f32_e32 v9, v8
	s_nop 0
	v_fma_f32 v10, -v8, v9, 1.0
	v_fmac_f32_e32 v9, v10, v9
	v_div_scale_f32 v10, vcc, 1.0, v7, 1.0
	v_mul_f32_e32 v11, v10, v9
	v_fma_f32 v12, -v8, v11, v10
	v_fmac_f32_e32 v11, v12, v9
	v_fma_f32 v8, -v8, v11, v10
	v_div_fmas_f32 v8, v8, v9, v11
	v_div_fixup_f32 v7, v8, v7, 1.0
	v_div_scale_f32 v8, s[8:9], v6, v6, 1.0
	v_rcp_f32_e32 v9, v8
	s_nop 0
	v_fma_f32 v10, -v8, v9, 1.0
	v_fmac_f32_e32 v9, v10, v9
	v_div_scale_f32 v10, vcc, 1.0, v6, 1.0
	v_mul_f32_e32 v11, v10, v9
	v_fma_f32 v12, -v8, v11, v10
	v_fmac_f32_e32 v11, v12, v9
	v_fma_f32 v8, -v8, v11, v10
	v_div_fmas_f32 v8, v8, v9, v11
	v_div_fixup_f32 v6, v8, v6, 1.0
	v_pk_mul_f32 v[4:5], v[4:5], v[6:7]
	v_pk_fma_f32 v[6:7], v[22:23], v[96:97], 0 op_sel_hi:[1,1,0]
	s_nop 0
	v_pk_fma_f32 v[6:7], v[26:27], v[98:99], v[6:7]
	s_nop 0
	v_pk_fma_f32 v[6:7], v[30:31], v[100:101], v[6:7]
	s_nop 0
	v_pk_fma_f32 v[6:7], v[34:35], v[102:103], v[6:7]
	s_nop 0
	v_mul_f32_e32 v8, 0xbfb8aa3b, v7
	v_exp_f32_e32 v9, v8
	v_mul_f32_e32 v8, 0xbfb8aa3b, v6
	v_exp_f32_e32 v8, v8
	s_nop 0
	v_pk_add_f32 v[8:9], v[8:9], 1.0 op_sel_hi:[1,0]
	s_nop 0
	v_div_scale_f32 v10, s[8:9], v9, v9, 1.0
	v_rcp_f32_e32 v11, v10
	s_nop 0
	v_fma_f32 v12, -v10, v11, 1.0
	v_fmac_f32_e32 v11, v12, v11
	v_div_scale_f32 v12, vcc, 1.0, v9, 1.0
	v_mul_f32_e32 v13, v12, v11
	v_fma_f32 v14, -v10, v13, v12
	v_fmac_f32_e32 v13, v14, v11
	v_fma_f32 v10, -v10, v13, v12
	v_div_fmas_f32 v10, v10, v11, v13
	v_div_fixup_f32 v9, v10, v9, 1.0
	v_div_scale_f32 v10, s[8:9], v8, v8, 1.0
	v_rcp_f32_e32 v11, v10
	s_nop 0
	v_fma_f32 v12, -v10, v11, 1.0
	v_fmac_f32_e32 v11, v12, v11
	v_div_scale_f32 v12, vcc, 1.0, v8, 1.0
	v_mul_f32_e32 v13, v12, v11
	v_fma_f32 v14, -v10, v13, v12
	v_fmac_f32_e32 v13, v14, v11
	v_fma_f32 v10, -v10, v13, v12
	v_div_fmas_f32 v10, v10, v11, v13
	v_div_fixup_f32 v8, v10, v8, 1.0
	v_pk_mul_f32 v[6:7], v[6:7], v[8:9]
	ds_write_b128 v240, v[4:7] offset:32784
	ds_write_b128 v241, v[0:3] offset:32768
	ds_write_b128 v241, v[36:39] offset:32784
	s_waitcnt lgkmcnt(0)
	s_barrier
; __device__ __forceinline__ void prepB(const Params& p, int h, int n, char* shmc, int tid, int wv) {
;     ...
;   {
;     const int lane = tid & 63, r = lane & 15, quad = lane >> 4, mt = wv & 3, ntb = (wv >> 2) * 2;
;     f32x4 aK[2] = {{0.f, 0.f, 0.f, 0.f}, {0.f, 0.f, 0.f, 0.f}}, aQ[2] = {{0.f, 0.f, 0.f, 0.f}, {0.f, 0.f, 0.f, 0.f}};
; #pragma unroll
;     for (int kk = 0; kk < 4; ++kk) {
;       const bf16x8 ak = *(const bf16x8*)&kB[(16 * mt + r) * 136 + kk * 32 + quad * 8];
;       const bf16x8 aq = *(const bf16x8*)&qB[(16 * mt + r) * 136 + kk * 32 + quad * 8];
; #pragma unroll
;       for (int i = 0; i < 2; ++i) {
;         const bf16x8 b = *(const bf16x8*)&kB[(16 * (ntb + i) + r) * 136 + kk * 32 + quad * 8];
;         aK[i] = __builtin_amdgcn_mfma_f32_16x16x32_bf16(ak, b, aK[i], 0, 0, 0);
;         aQ[i] = __builtin_amdgcn_mfma_f32_16x16x32_bf16(aq, b, aQ[i], 0, 0, 0);
;       }
;     }
; #pragma unroll
;     for (int i = 0; i < 2; ++i)
; #pragma unroll
;       for (int j = 0; j < 4; ++j) {
;         const int t = 16 * mt + 4 * quad + j, s = 16 * (ntb + i) + r;
;         const float dec = (s <= t) ? __expf(gcS[t] - gcS[s]) : 0.f;
	ds_read_b128 v[0:3], v167
	ds_read_b128 v[4:7], v168
	ds_read_b128 v[8:11], v28
	ds_read_b128 v[16:19], v29
	s_waitcnt lgkmcnt(1)
	v_mfma_f32_16x16x32_bf16 v[12:15], v[0:3], v[8:11], 0
	v_mfma_f32_16x16x32_bf16 v[8:11], v[4:7], v[8:11], 0
	s_waitcnt lgkmcnt(0)
	v_mfma_f32_16x16x32_bf16 v[0:3], v[0:3], v[16:19], 0
	v_mfma_f32_16x16x32_bf16 v[4:7], v[4:7], v[16:19], 0
	ds_read_b128 v[16:19], v170
	ds_read_b128 v[20:23], v171
	ds_read_b128 v[24:27], v28 offset:64
	s_waitcnt lgkmcnt(0)
	v_mfma_f32_16x16x32_bf16 v[12:15], v[16:19], v[24:27], v[12:15]
	v_mfma_f32_16x16x32_bf16 v[8:11], v[20:23], v[24:27], v[8:11]
	ds_read_b128 v[24:27], v29 offset:64
	s_waitcnt lgkmcnt(0)
	v_mfma_f32_16x16x32_bf16 v[0:3], v[16:19], v[24:27], v[0:3]
	v_mfma_f32_16x16x32_bf16 v[4:7], v[20:23], v[24:27], v[4:7]
	ds_read_b128 v[16:19], v172
	ds_read_b128 v[20:23], v173
	ds_read_b128 v[24:27], v28 offset:128
	s_waitcnt lgkmcnt(0)
	v_mfma_f32_16x16x32_bf16 v[12:15], v[16:19], v[24:27], v[12:15]
	v_mfma_f32_16x16x32_bf16 v[8:11], v[20:23], v[24:27], v[8:11]
	ds_read_b128 v[24:27], v29 offset:128
	s_waitcnt lgkmcnt(0)
	v_mfma_f32_16x16x32_bf16 v[0:3], v[16:19], v[24:27], v[0:3]
	v_mfma_f32_16x16x32_bf16 v[16:19], v[20:23], v[24:27], v[4:7]
	s_nop 2
	ds_read_b128 v[4:7], v174
	ds_read_b128 v[20:23], v175
	ds_read_b128 v[24:27], v28 offset:192
	s_waitcnt lgkmcnt(0)
	v_mfma_f32_16x16x32_bf16 v[12:15], v[4:7], v[24:27], v[12:15]
	v_mfma_f32_16x16x32_bf16 v[8:11], v[20:23], v[24:27], v[8:11]
	ds_read_b128 v[24:27], v29 offset:192
	s_waitcnt lgkmcnt(0)
	v_mfma_f32_16x16x32_bf16 v[4:7], v[4:7], v[24:27], v[0:3]
	v_mfma_f32_16x16x32_bf16 v[0:3], v[20:23], v[24:27], v[16:19]
	s_and_saveexec_b64 s[76:77], s[24:25]
	s_cbranch_execz .LBB0_468
	s_nop 0
	ds_read_b32 v16, v177
	ds_read_b32 v17, v176
	s_waitcnt lgkmcnt(0)
	v_sub_f32_e32 v16, v16, v17
	v_mul_f32_e32 v16, 0x3fb8aa3b, v16
	v_exp_f32_e32 v85, v16

; __device__ __forceinline__ void prepB(const Params& p, int h, int n, char* shmc, int tid, int wv) {
;     ...
; #pragma unroll 4
;       for (int s = 0; s < 16 * bi; ++s) {
;         const float xs = X[s * 128 + c];
;         const float4 m0 = *(const float4*)&Mm[s * 64 + 16 * bi], m1 = *(const float4*)&Mm[s * 64 + 16 * bi + 4],
;                      m2 = *(const float4*)&Mm[s * 64 + 16 * bi + 8], m3 = *(const float4*)&Mm[s * 64 + 16 * bi + 12];
;         acc[0] -= m0.x * xs; acc[1] -= m0.y * xs; acc[2] -= m0.z * xs; acc[3] -= m0.w * xs;
;         acc[4] -= m1.x * xs; acc[5] -= m1.y * xs; acc[6] -= m1.z * xs; acc[7] -= m1.w * xs;
;         acc[8] -= m2.x * xs; acc[9] -= m2.y * xs; acc[10] -= m2.z * xs; acc[11] -= m2.w * xs;
;         acc[12] -= m3.x * xs; acc[13] -= m3.y * xs; acc[14] -= m3.z * xs; acc[15] -= m3.w * xs;
;       }
.LBB0_535:
	s_or_b64 exec, exec, s[76:77]
	s_cmp_eq_u32 s61, 0
	s_cbranch_scc1 .LBB0_502
	s_max_u32 s77, s13, 1
	s_and_b32 s8, s77, -16
	s_mov_b32 s9, 0
	s_mov_b32 s76, s59
	v_mov_b32_e32 v8, v195
	v_mov_b32_e32 v9, s76
	ds_read2st64_b32 v[26:27], v8 offset1:2
	ds_read_b128 v[120:123], v9
	ds_read_b128 v[124:127], v9 offset:16
	ds_read_b128 v[128:131], v9 offset:32
	ds_read_b128 v[132:135], v9 offset:48
.LBB0_537:
	ds_read_b128 v[136:139], v9 offset:256
	ds_read_b128 v[144:147], v9 offset:272
	ds_read_b128 v[148:151], v9 offset:288
	ds_read_b128 v[152:155], v9 offset:304
	s_add_i32 s9, s9, 4
	s_addk_i32 s76, 0x400
	s_waitcnt lgkmcnt(4)
	v_pk_fma_f32 v[6:7], v[26:27], v[122:123], v[6:7] op_sel_hi:[0,1,1] neg_lo:[1,0,0] neg_hi:[1,0,0]
	v_pk_fma_f32 v[2:3], v[26:27], v[126:127], v[2:3] op_sel_hi:[0,1,1] neg_lo:[1,0,0] neg_hi:[1,0,0]
	v_pk_fma_f32 v[94:95], v[26:27], v[130:131], v[94:95] op_sel_hi:[0,1,1] neg_lo:[1,0,0] neg_hi:[1,0,0]
	v_pk_fma_f32 v[12:13], v[26:27], v[134:135], v[12:13] op_sel_hi:[0,1,1] neg_lo:[1,0,0] neg_hi:[1,0,0]
	v_pk_fma_f32 v[0:1], v[26:27], v[124:125], v[0:1] op_sel_hi:[0,1,1] neg_lo:[1,0,0] neg_hi:[1,0,0]
	v_pk_fma_f32 v[4:5], v[26:27], v[128:129], v[4:5] op_sel_hi:[0,1,1] neg_lo:[1,0,0] neg_hi:[1,0,0]
	v_pk_fma_f32 v[32:33], v[26:27], v[120:121], v[32:33] op_sel_hi:[0,1,1] neg_lo:[1,0,0] neg_hi:[1,0,0]
	v_pk_fma_f32 v[34:35], v[26:27], v[132:133], v[34:35] op_sel_hi:[0,1,1] neg_lo:[1,0,0] neg_hi:[1,0,0]
	v_mov_b32_e32 v26, v27
	ds_read2st64_b32 v[38:39], v8 offset0:4 offset1:6
	ds_read_b128 v[120:123], v9 offset:512
	ds_read_b128 v[124:127], v9 offset:528
	ds_read_b128 v[128:131], v9 offset:544
	ds_read_b128 v[132:135], v9 offset:560
	s_waitcnt lgkmcnt(5)
	v_pk_fma_f32 v[6:7], v[26:27], v[138:139], v[6:7] op_sel_hi:[0,1,1] neg_lo:[1,0,0] neg_hi:[1,0,0]
	v_pk_fma_f32 v[2:3], v[26:27], v[146:147], v[2:3] op_sel_hi:[0,1,1] neg_lo:[1,0,0] neg_hi:[1,0,0]
	v_pk_fma_f32 v[94:95], v[26:27], v[150:151], v[94:95] op_sel_hi:[0,1,1] neg_lo:[1,0,0] neg_hi:[1,0,0]
	v_pk_fma_f32 v[12:13], v[26:27], v[154:155], v[12:13] op_sel_hi:[0,1,1] neg_lo:[1,0,0] neg_hi:[1,0,0]
	v_pk_fma_f32 v[0:1], v[26:27], v[144:145], v[0:1] op_sel_hi:[0,1,1] neg_lo:[1,0,0] neg_hi:[1,0,0]
	v_pk_fma_f32 v[4:5], v[26:27], v[148:149], v[4:5] op_sel_hi:[0,1,1] neg_lo:[1,0,0] neg_hi:[1,0,0]
	v_pk_fma_f32 v[32:33], v[26:27], v[136:137], v[32:33] op_sel_hi:[0,1,1] neg_lo:[1,0,0] neg_hi:[1,0,0]
	v_pk_fma_f32 v[34:35], v[26:27], v[152:153], v[34:35] op_sel_hi:[0,1,1] neg_lo:[1,0,0] neg_hi:[1,0,0]
	ds_read_b128 v[136:139], v9 offset:768
	ds_read_b128 v[144:147], v9 offset:784
	ds_read_b128 v[148:151], v9 offset:800
	ds_read_b128 v[152:155], v9 offset:816
	v_add_u32_e32 v8, 0x800, v8
	s_waitcnt lgkmcnt(4)
	v_pk_fma_f32 v[6:7], v[38:39], v[122:123], v[6:7] op_sel_hi:[0,1,1] neg_lo:[1,0,0] neg_hi:[1,0,0]
	v_pk_fma_f32 v[2:3], v[38:39], v[126:127], v[2:3] op_sel_hi:[0,1,1] neg_lo:[1,0,0] neg_hi:[1,0,0]
	v_pk_fma_f32 v[94:95], v[38:39], v[130:131], v[94:95] op_sel_hi:[0,1,1] neg_lo:[1,0,0] neg_hi:[1,0,0]
	v_pk_fma_f32 v[12:13], v[38:39], v[134:135], v[12:13] op_sel_hi:[0,1,1] neg_lo:[1,0,0] neg_hi:[1,0,0]
	v_pk_fma_f32 v[0:1], v[38:39], v[124:125], v[0:1] op_sel_hi:[0,1,1] neg_lo:[1,0,0] neg_hi:[1,0,0]
	v_pk_fma_f32 v[4:5], v[38:39], v[128:129], v[4:5] op_sel_hi:[0,1,1] neg_lo:[1,0,0] neg_hi:[1,0,0]
	v_pk_fma_f32 v[32:33], v[38:39], v[120:121], v[32:33] op_sel_hi:[0,1,1] neg_lo:[1,0,0] neg_hi:[1,0,0]
	v_pk_fma_f32 v[34:35], v[38:39], v[132:133], v[34:35] op_sel_hi:[0,1,1] neg_lo:[1,0,0] neg_hi:[1,0,0]
	v_mov_b32_e32 v38, v39
	v_mov_b32_e32 v9, s76
	ds_read2st64_b32 v[26:27], v8 offset1:2
	ds_read_b128 v[120:123], v9
	ds_read_b128 v[124:127], v9 offset:16
	ds_read_b128 v[128:131], v9 offset:32
	ds_read_b128 v[132:135], v9 offset:48
	s_waitcnt lgkmcnt(5)
	v_pk_fma_f32 v[6:7], v[38:39], v[138:139], v[6:7] op_sel_hi:[0,1,1] neg_lo:[1,0,0] neg_hi:[1,0,0]
	v_pk_fma_f32 v[2:3], v[38:39], v[146:147], v[2:3] op_sel_hi:[0,1,1] neg_lo:[1,0,0] neg_hi:[1,0,0]
	v_pk_fma_f32 v[94:95], v[38:39], v[150:151], v[94:95] op_sel_hi:[0,1,1] neg_lo:[1,0,0] neg_hi:[1,0,0]
	v_pk_fma_f32 v[12:13], v[38:39], v[154:155], v[12:13] op_sel_hi:[0,1,1] neg_lo:[1,0,0] neg_hi:[1,0,0]
	v_pk_fma_f32 v[0:1], v[38:39], v[144:145], v[0:1] op_sel_hi:[0,1,1] neg_lo:[1,0,0] neg_hi:[1,0,0]
	v_pk_fma_f32 v[4:5], v[38:39], v[148:149], v[4:5] op_sel_hi:[0,1,1] neg_lo:[1,0,0] neg_hi:[1,0,0]
	v_pk_fma_f32 v[32:33], v[38:39], v[136:137], v[32:33] op_sel_hi:[0,1,1] neg_lo:[1,0,0] neg_hi:[1,0,0]
	v_pk_fma_f32 v[34:35], v[38:39], v[152:153], v[34:35] op_sel_hi:[0,1,1] neg_lo:[1,0,0] neg_hi:[1,0,0]
	s_cmp_lg_u32 s8, s9
	s_cbranch_scc1 .LBB0_537
	s_waitcnt lgkmcnt(0)
	s_max_u32 s8, s93, 1
	s_bitcmp0_b32 s8, 0
	s_cbranch_scc1 .LBB0_502
	s_and_b32 s8, s77, 1
	s_lshl_b32 s8, s8, 8
	s_mov_b32 s9, 0
	s_mov_b32 s77, 0
